# gl1 front end: pack kt/qt into one cvt_pk (d16_hi store), d16_hi q/k loads for scan groups 2-3 (no unpack shift), log term as single f32 fmac ln2*log2(1+e)+max
# speedup vs baseline: 1.0124x; 1.0040x over previous
; __device__ __forceinline__ unsigned pk2(float lo, float hi) { unsigned r; asm("v_cvt_pk_bf16_f32 %0, %1, %2" : "=v"(r) : "v"(lo), "v"(hi)); return r; }
; __device__ __forceinline__ void gl1_item(PREF p, int l, int item, bool valid, LAS unsigned char* pl, int sw, int lane) {
;     ...
;         unsigned wupp[8];
; #pragma unroll
;         for (int r2 = 0; r2 < 8; ++r2) wupp[r2] = pk2(p.gla_wup[(size_t)((l * 2 + d) * 16 + 2 * r2) * 256 + h * 64 + lane], p.gla_wup[(size_t)((l * 2 + d) * 16 + 2 * r2 + 1) * 256 + h * 64 + lane]);
;         const float bup = p.gla_bup[(l * 2 + d) * 256 + h * 64 + lane];
; #pragma unroll 1
;         for (int g2 = 0; g2 < 2; ++g2) {
;             unsigned vr[16];
; #pragma unroll
;             for (int ii = 0; ii < 16; ++ii) { const int i = 32 * sw + g2 * 16 + ii; vr[ii] = *(const unsigned*)(P + (size_t)(row0 + i * rstride) * PW + 1536 + h * 128 + 2 * lane); }
; #pragma unroll
;             for (int ii = 0; ii < 16; ++ii) { const int i = 32 * sw + g2 * 16 + ii; sVt[(2 * lane) * 72 + i] = (bf16_t)(vr[ii] & 0xffffu); sVt[(2 * lane + 1) * 72 + i] = (bf16_t)(vr[ii] >> 16); }
;         }
;         float bc = 0.f;
; #pragma unroll 1
;         for (int g4 = 0; g4 < 4; ++g4) {
;             float qn[16], kn[16];
;             if (g4 < 3) {
; #pragma unroll
;                 for (int ss = 0; ss < 16; ++ss) { const int s = (g4 + 1) * 16 + ss; const int i = d ? 63 - s : s; const bf16_t* pr = P + (size_t)(row0 + i * rstride) * PW + h * 64 + lane;
;                     qn[ss] = __builtin_bit_cast(float, (unsigned)pr[1024]); kn[ss] = __builtin_bit_cast(float, (unsigned)pr[1280]); }
;                 __builtin_amdgcn_sched_barrier(0);
;             }
;             float gv[16];
; #pragma unroll
;             for (int ss = 0; ss < 16; ++ss) { const int s = g4 * 16 + ss; const int i = d ? 63 - s : s;
;                 float z = bup;
; #pragma unroll
;                 for (int r2 = 0; r2 < 8; ++r2) { const unsigned w = (unsigned)__builtin_amdgcn_readlane((int)lrp[r2], i);
;                     z = __builtin_amdgcn_fdot2_f32_bf16(__builtin_bit_cast(bf16x2_t, w), __builtin_bit_cast(bf16x2_t, wupp[r2]), z, false); }
.Lgl1v_fwd:
	s_mul_i32 s45, s46, 0x2400
	s_add_i32 s45, s45, s47
	s_add_i32 s45, s45, 0x4800
	s_lshl_b32 s50, s30, 1
	s_add_i32 s45, s45, s50
	s_movk_i32 s50, 0x90
	v_mul_u32_u24_e32 v60, 0x90, v64
	v_add_u32_e32 v60, s45, v60
	s_lshl_b32 s50, s2, 1
	v_mov_b32_e32 v61, s50
	s_waitcnt vmcnt(32)
	v_cvt_pk_bf16_f32 v8, v90, v91
	v_cvt_pk_bf16_f32 v9, v92, v93
	v_cvt_pk_bf16_f32 v10, v94, v95
	v_cvt_pk_bf16_f32 v11, v96, v97
	v_cvt_pk_bf16_f32 v12, v98, v99
	v_cvt_pk_bf16_f32 v13, v100, v101
	v_cvt_pk_bf16_f32 v14, v102, v103
	v_cvt_pk_bf16_f32 v15, v104, v105
	s_waitcnt vmcnt(0)
	v_mul_u32_u24_e32 v86, 0x120, v64
	s_lshl_b32 s45, s46, 6
	s_add_i32 s45, s45, s47
	v_add_u32_e32 v86, s45, v86
	ds_write_b16 v86, v34 offset:0
	ds_write_b16_d16_hi v86, v34 offset:144
	ds_write_b16 v86, v35 offset:2
	ds_write_b16_d16_hi v86, v35 offset:146
	ds_write_b16 v86, v36 offset:4
	ds_write_b16_d16_hi v86, v36 offset:148
	ds_write_b16 v86, v37 offset:6
	ds_write_b16_d16_hi v86, v37 offset:150
	ds_write_b16 v86, v38 offset:8
	ds_write_b16_d16_hi v86, v38 offset:152
	ds_write_b16 v86, v39 offset:10
	ds_write_b16_d16_hi v86, v39 offset:154
	ds_write_b16 v86, v40 offset:12
	ds_write_b16_d16_hi v86, v40 offset:156
	ds_write_b16 v86, v41 offset:14
	ds_write_b16_d16_hi v86, v41 offset:158
	ds_write_b16 v86, v42 offset:16
	ds_write_b16_d16_hi v86, v42 offset:160
	ds_write_b16 v86, v43 offset:18
	ds_write_b16_d16_hi v86, v43 offset:162
	ds_write_b16 v86, v44 offset:20
	ds_write_b16_d16_hi v86, v44 offset:164
	ds_write_b16 v86, v45 offset:22
	ds_write_b16_d16_hi v86, v45 offset:166
	ds_write_b16 v86, v46 offset:24
	ds_write_b16_d16_hi v86, v46 offset:168
	ds_write_b16 v86, v47 offset:26
	ds_write_b16_d16_hi v86, v47 offset:170
	ds_write_b16 v86, v212 offset:28
	ds_write_b16_d16_hi v86, v212 offset:172
	ds_write_b16 v86, v213 offset:30
	ds_write_b16_d16_hi v86, v213 offset:174
	ds_write_b16 v86, v214 offset:32
	ds_write_b16_d16_hi v86, v214 offset:176
	ds_write_b16 v86, v215 offset:34
	ds_write_b16_d16_hi v86, v215 offset:178
	ds_write_b16 v86, v216 offset:36
	ds_write_b16_d16_hi v86, v216 offset:180
	ds_write_b16 v86, v217 offset:38
	ds_write_b16_d16_hi v86, v217 offset:182
	ds_write_b16 v86, v218 offset:40
	ds_write_b16_d16_hi v86, v218 offset:184
	ds_write_b16 v86, v219 offset:42
	ds_write_b16_d16_hi v86, v219 offset:186
	ds_write_b16 v86, v222 offset:44
	ds_write_b16_d16_hi v86, v222 offset:188
	ds_write_b16 v86, v223 offset:46
	ds_write_b16_d16_hi v86, v223 offset:190
	ds_write_b16 v86, v228 offset:48
	ds_write_b16_d16_hi v86, v228 offset:192
	ds_write_b16 v86, v229 offset:50
	ds_write_b16_d16_hi v86, v229 offset:194
	ds_write_b16 v86, v230 offset:52
	ds_write_b16_d16_hi v86, v230 offset:196
	ds_write_b16 v86, v231 offset:54
	ds_write_b16_d16_hi v86, v231 offset:198
	ds_write_b16 v86, v232 offset:56
	ds_write_b16_d16_hi v86, v232 offset:200
	ds_write_b16 v86, v233 offset:58
	ds_write_b16_d16_hi v86, v233 offset:202
	ds_write_b16 v86, v234 offset:60
	ds_write_b16_d16_hi v86, v234 offset:204
	ds_write_b16 v86, v235 offset:62
	ds_write_b16_d16_hi v86, v235 offset:206
	global_load_ushort v148, v134, s[6:7]
	global_load_ushort v164, v134, s[6:7] offset:512
	s_add_u32 s6, s6, s54
	s_addc_u32 s7, s7, s55
	global_load_ushort v149, v134, s[6:7]
	global_load_ushort v165, v134, s[6:7] offset:512
	s_add_u32 s6, s6, s54
	s_addc_u32 s7, s7, s55
	global_load_ushort v150, v134, s[6:7]
	global_load_ushort v166, v134, s[6:7] offset:512
	s_add_u32 s6, s6, s54
	s_addc_u32 s7, s7, s55
	global_load_ushort v151, v134, s[6:7]
	global_load_ushort v167, v134, s[6:7] offset:512
	s_add_u32 s6, s6, s54
	s_addc_u32 s7, s7, s55
	global_load_ushort v152, v134, s[6:7]
	global_load_ushort v168, v134, s[6:7] offset:512
	s_add_u32 s6, s6, s54
	s_addc_u32 s7, s7, s55
	global_load_ushort v153, v134, s[6:7]
	global_load_ushort v169, v134, s[6:7] offset:512
	s_add_u32 s6, s6, s54
	s_addc_u32 s7, s7, s55
	global_load_ushort v154, v134, s[6:7]
	global_load_ushort v170, v134, s[6:7] offset:512
	s_add_u32 s6, s6, s54
	s_addc_u32 s7, s7, s55
	global_load_ushort v155, v134, s[6:7]
	global_load_ushort v171, v134, s[6:7] offset:512
	s_add_u32 s6, s6, s54
	s_addc_u32 s7, s7, s55
	global_load_ushort v156, v134, s[6:7]
	global_load_ushort v172, v134, s[6:7] offset:512
	s_add_u32 s6, s6, s54
	s_addc_u32 s7, s7, s55
	global_load_ushort v157, v134, s[6:7]
	global_load_ushort v173, v134, s[6:7] offset:512
	s_add_u32 s6, s6, s54
	s_addc_u32 s7, s7, s55
	global_load_ushort v158, v134, s[6:7]
	global_load_ushort v174, v134, s[6:7] offset:512
	s_add_u32 s6, s6, s54
	s_addc_u32 s7, s7, s55
	global_load_ushort v159, v134, s[6:7]
	global_load_ushort v175, v134, s[6:7] offset:512
	s_add_u32 s6, s6, s54
	s_addc_u32 s7, s7, s55
	global_load_ushort v160, v134, s[6:7]
	global_load_ushort v176, v134, s[6:7] offset:512
	s_add_u32 s6, s6, s54
	s_addc_u32 s7, s7, s55
	global_load_ushort v161, v134, s[6:7]
	global_load_ushort v177, v134, s[6:7] offset:512
	s_add_u32 s6, s6, s54
	s_addc_u32 s7, s7, s55
	global_load_ushort v162, v134, s[6:7]
	global_load_ushort v178, v134, s[6:7] offset:512
	s_add_u32 s6, s6, s54
	s_addc_u32 s7, s7, s55
	global_load_ushort v163, v134, s[6:7]
	global_load_ushort v179, v134, s[6:7] offset:512
	s_add_u32 s6, s6, s54
	s_addc_u32 s7, s7, s55
	v_mov_b32_e32 v17, 0
	s_mov_b32 s1, 0xbfb8aa3b
	s_mov_b32 s49, 0xbd800000
	v_mov_b32_e32 v236, v16
	v_dot2c_f32_bf16_dpp v236, v0, v8 row_newbcast:0 row_mask:0xf bank_mask:0xf
	v_dot2c_f32_bf16_dpp v236, v1, v9 row_newbcast:0 row_mask:0xf bank_mask:0xf
	v_dot2c_f32_bf16_dpp v236, v2, v10 row_newbcast:0 row_mask:0xf bank_mask:0xf
; __device__ __forceinline__ void gl1_item(PREF p, int l, int item, bool valid, LAS unsigned char* pl, int sw, int lane) {
;     ...
;             for (int ss = 0; ss < 16; ++ss) { const int s = g4 * 16 + ss; const int i = d ? 63 - s : s;
;                 float z = bup;
; #pragma unroll
;                 for (int r2 = 0; r2 < 8; ++r2) { const unsigned w = (unsigned)__builtin_amdgcn_readlane((int)lrp[r2], i);
;                     z = __builtin_amdgcn_fdot2_f32_bf16(__builtin_bit_cast(bf16x2_t, w), __builtin_bit_cast(bf16x2_t, wupp[r2]), z, false); }
;                 gv[ss] = -(fmaxf(-z, 0.f) + __logf(1.f + __expf(-fabsf(z)))) * (1.f / 16.f);
	v_dot2c_f32_bf16_dpp v236, v3, v11 row_newbcast:0 row_mask:0xf bank_mask:0xf
	v_dot2c_f32_bf16_dpp v236, v4, v12 row_newbcast:0 row_mask:0xf bank_mask:0xf
	v_dot2c_f32_bf16_dpp v236, v5, v13 row_newbcast:0 row_mask:0xf bank_mask:0xf
	v_dot2c_f32_bf16_dpp v236, v6, v14 row_newbcast:0 row_mask:0xf bank_mask:0xf
	v_dot2c_f32_bf16_dpp v236, v7, v15 row_newbcast:0 row_mask:0xf bank_mask:0xf
	v_mov_b32_e32 v237, v16
	v_dot2c_f32_bf16_dpp v237, v0, v8 row_newbcast:1 row_mask:0xf bank_mask:0xf
	v_dot2c_f32_bf16_dpp v237, v1, v9 row_newbcast:1 row_mask:0xf bank_mask:0xf
	v_dot2c_f32_bf16_dpp v237, v2, v10 row_newbcast:1 row_mask:0xf bank_mask:0xf
	v_dot2c_f32_bf16_dpp v237, v3, v11 row_newbcast:1 row_mask:0xf bank_mask:0xf
	v_dot2c_f32_bf16_dpp v237, v4, v12 row_newbcast:1 row_mask:0xf bank_mask:0xf
	v_dot2c_f32_bf16_dpp v237, v5, v13 row_newbcast:1 row_mask:0xf bank_mask:0xf
	v_dot2c_f32_bf16_dpp v237, v6, v14 row_newbcast:1 row_mask:0xf bank_mask:0xf
	v_dot2c_f32_bf16_dpp v237, v7, v15 row_newbcast:1 row_mask:0xf bank_mask:0xf
	v_mov_b32_e32 v238, v16
	v_dot2c_f32_bf16_dpp v238, v0, v8 row_newbcast:2 row_mask:0xf bank_mask:0xf
	v_dot2c_f32_bf16_dpp v238, v1, v9 row_newbcast:2 row_mask:0xf bank_mask:0xf
	v_dot2c_f32_bf16_dpp v238, v2, v10 row_newbcast:2 row_mask:0xf bank_mask:0xf
	v_dot2c_f32_bf16_dpp v238, v3, v11 row_newbcast:2 row_mask:0xf bank_mask:0xf
	v_dot2c_f32_bf16_dpp v238, v4, v12 row_newbcast:2 row_mask:0xf bank_mask:0xf
	v_dot2c_f32_bf16_dpp v238, v5, v13 row_newbcast:2 row_mask:0xf bank_mask:0xf
	v_dot2c_f32_bf16_dpp v238, v6, v14 row_newbcast:2 row_mask:0xf bank_mask:0xf
	v_dot2c_f32_bf16_dpp v238, v7, v15 row_newbcast:2 row_mask:0xf bank_mask:0xf
	v_mov_b32_e32 v239, v16
	v_dot2c_f32_bf16_dpp v239, v0, v8 row_newbcast:3 row_mask:0xf bank_mask:0xf
	v_dot2c_f32_bf16_dpp v239, v1, v9 row_newbcast:3 row_mask:0xf bank_mask:0xf
	v_dot2c_f32_bf16_dpp v239, v2, v10 row_newbcast:3 row_mask:0xf bank_mask:0xf
	v_dot2c_f32_bf16_dpp v239, v3, v11 row_newbcast:3 row_mask:0xf bank_mask:0xf
	v_dot2c_f32_bf16_dpp v239, v4, v12 row_newbcast:3 row_mask:0xf bank_mask:0xf
	v_dot2c_f32_bf16_dpp v239, v5, v13 row_newbcast:3 row_mask:0xf bank_mask:0xf
	v_dot2c_f32_bf16_dpp v239, v6, v14 row_newbcast:3 row_mask:0xf bank_mask:0xf
	v_dot2c_f32_bf16_dpp v239, v7, v15 row_newbcast:3 row_mask:0xf bank_mask:0xf
	v_mov_b32_e32 v240, v16
	v_dot2c_f32_bf16_dpp v240, v0, v8 row_newbcast:4 row_mask:0xf bank_mask:0xf
	v_dot2c_f32_bf16_dpp v240, v1, v9 row_newbcast:4 row_mask:0xf bank_mask:0xf
	v_dot2c_f32_bf16_dpp v240, v2, v10 row_newbcast:4 row_mask:0xf bank_mask:0xf
	v_dot2c_f32_bf16_dpp v240, v3, v11 row_newbcast:4 row_mask:0xf bank_mask:0xf
	v_dot2c_f32_bf16_dpp v240, v4, v12 row_newbcast:4 row_mask:0xf bank_mask:0xf
	v_dot2c_f32_bf16_dpp v240, v5, v13 row_newbcast:4 row_mask:0xf bank_mask:0xf
	v_dot2c_f32_bf16_dpp v240, v6, v14 row_newbcast:4 row_mask:0xf bank_mask:0xf
	v_dot2c_f32_bf16_dpp v240, v7, v15 row_newbcast:4 row_mask:0xf bank_mask:0xf
	v_mov_b32_e32 v241, v16
	v_dot2c_f32_bf16_dpp v241, v0, v8 row_newbcast:5 row_mask:0xf bank_mask:0xf
	v_dot2c_f32_bf16_dpp v241, v1, v9 row_newbcast:5 row_mask:0xf bank_mask:0xf
	v_dot2c_f32_bf16_dpp v241, v2, v10 row_newbcast:5 row_mask:0xf bank_mask:0xf
	v_dot2c_f32_bf16_dpp v241, v3, v11 row_newbcast:5 row_mask:0xf bank_mask:0xf
	v_dot2c_f32_bf16_dpp v241, v4, v12 row_newbcast:5 row_mask:0xf bank_mask:0xf
	v_dot2c_f32_bf16_dpp v241, v5, v13 row_newbcast:5 row_mask:0xf bank_mask:0xf
	v_dot2c_f32_bf16_dpp v241, v6, v14 row_newbcast:5 row_mask:0xf bank_mask:0xf
	v_dot2c_f32_bf16_dpp v241, v7, v15 row_newbcast:5 row_mask:0xf bank_mask:0xf
	v_mov_b32_e32 v242, v16
	v_dot2c_f32_bf16_dpp v242, v0, v8 row_newbcast:6 row_mask:0xf bank_mask:0xf
	v_dot2c_f32_bf16_dpp v242, v1, v9 row_newbcast:6 row_mask:0xf bank_mask:0xf
	v_dot2c_f32_bf16_dpp v242, v2, v10 row_newbcast:6 row_mask:0xf bank_mask:0xf
	v_dot2c_f32_bf16_dpp v242, v3, v11 row_newbcast:6 row_mask:0xf bank_mask:0xf
	v_dot2c_f32_bf16_dpp v242, v4, v12 row_newbcast:6 row_mask:0xf bank_mask:0xf
	v_dot2c_f32_bf16_dpp v242, v5, v13 row_newbcast:6 row_mask:0xf bank_mask:0xf
	v_dot2c_f32_bf16_dpp v242, v6, v14 row_newbcast:6 row_mask:0xf bank_mask:0xf
	v_dot2c_f32_bf16_dpp v242, v7, v15 row_newbcast:6 row_mask:0xf bank_mask:0xf
	v_mov_b32_e32 v243, v16
	v_dot2c_f32_bf16_dpp v243, v0, v8 row_newbcast:7 row_mask:0xf bank_mask:0xf
	v_dot2c_f32_bf16_dpp v243, v1, v9 row_newbcast:7 row_mask:0xf bank_mask:0xf
	v_dot2c_f32_bf16_dpp v243, v2, v10 row_newbcast:7 row_mask:0xf bank_mask:0xf
	v_dot2c_f32_bf16_dpp v243, v3, v11 row_newbcast:7 row_mask:0xf bank_mask:0xf
	v_dot2c_f32_bf16_dpp v243, v4, v12 row_newbcast:7 row_mask:0xf bank_mask:0xf
	v_dot2c_f32_bf16_dpp v243, v5, v13 row_newbcast:7 row_mask:0xf bank_mask:0xf
	v_dot2c_f32_bf16_dpp v243, v6, v14 row_newbcast:7 row_mask:0xf bank_mask:0xf
	v_dot2c_f32_bf16_dpp v243, v7, v15 row_newbcast:7 row_mask:0xf bank_mask:0xf
	v_mov_b32_e32 v244, v16
	v_dot2c_f32_bf16_dpp v244, v0, v8 row_newbcast:8 row_mask:0xf bank_mask:0xf
	v_dot2c_f32_bf16_dpp v244, v1, v9 row_newbcast:8 row_mask:0xf bank_mask:0xf
	v_dot2c_f32_bf16_dpp v244, v2, v10 row_newbcast:8 row_mask:0xf bank_mask:0xf
	v_dot2c_f32_bf16_dpp v244, v3, v11 row_newbcast:8 row_mask:0xf bank_mask:0xf
	v_dot2c_f32_bf16_dpp v244, v4, v12 row_newbcast:8 row_mask:0xf bank_mask:0xf
	v_dot2c_f32_bf16_dpp v244, v5, v13 row_newbcast:8 row_mask:0xf bank_mask:0xf
	v_dot2c_f32_bf16_dpp v244, v6, v14 row_newbcast:8 row_mask:0xf bank_mask:0xf
	v_dot2c_f32_bf16_dpp v244, v7, v15 row_newbcast:8 row_mask:0xf bank_mask:0xf
	v_mov_b32_e32 v245, v16
	v_dot2c_f32_bf16_dpp v245, v0, v8 row_newbcast:9 row_mask:0xf bank_mask:0xf
; __device__ __forceinline__ void gl1_item(PREF p, int l, int item, bool valid, LAS unsigned char* pl, int sw, int lane) {
;     ...
;             for (int ss = 0; ss < 16; ++ss) { const int s = g4 * 16 + ss; const int i = d ? 63 - s : s;
;                 float z = bup;
; #pragma unroll
;                 for (int r2 = 0; r2 < 8; ++r2) { const unsigned w = (unsigned)__builtin_amdgcn_readlane((int)lrp[r2], i);
;                     z = __builtin_amdgcn_fdot2_f32_bf16(__builtin_bit_cast(bf16x2_t, w), __builtin_bit_cast(bf16x2_t, wupp[r2]), z, false); }
;                 gv[ss] = -(fmaxf(-z, 0.f) + __logf(1.f + __expf(-fabsf(z)))) * (1.f / 16.f);
	v_dot2c_f32_bf16_dpp v245, v1, v9 row_newbcast:9 row_mask:0xf bank_mask:0xf
	v_dot2c_f32_bf16_dpp v245, v2, v10 row_newbcast:9 row_mask:0xf bank_mask:0xf
	v_dot2c_f32_bf16_dpp v245, v3, v11 row_newbcast:9 row_mask:0xf bank_mask:0xf
	v_dot2c_f32_bf16_dpp v245, v4, v12 row_newbcast:9 row_mask:0xf bank_mask:0xf
	v_dot2c_f32_bf16_dpp v245, v5, v13 row_newbcast:9 row_mask:0xf bank_mask:0xf
	v_dot2c_f32_bf16_dpp v245, v6, v14 row_newbcast:9 row_mask:0xf bank_mask:0xf
	v_dot2c_f32_bf16_dpp v245, v7, v15 row_newbcast:9 row_mask:0xf bank_mask:0xf
	v_mov_b32_e32 v246, v16
	v_dot2c_f32_bf16_dpp v246, v0, v8 row_newbcast:10 row_mask:0xf bank_mask:0xf
	v_dot2c_f32_bf16_dpp v246, v1, v9 row_newbcast:10 row_mask:0xf bank_mask:0xf
	v_dot2c_f32_bf16_dpp v246, v2, v10 row_newbcast:10 row_mask:0xf bank_mask:0xf
	v_dot2c_f32_bf16_dpp v246, v3, v11 row_newbcast:10 row_mask:0xf bank_mask:0xf
	v_dot2c_f32_bf16_dpp v246, v4, v12 row_newbcast:10 row_mask:0xf bank_mask:0xf
	v_dot2c_f32_bf16_dpp v246, v5, v13 row_newbcast:10 row_mask:0xf bank_mask:0xf
	v_dot2c_f32_bf16_dpp v246, v6, v14 row_newbcast:10 row_mask:0xf bank_mask:0xf
	v_dot2c_f32_bf16_dpp v246, v7, v15 row_newbcast:10 row_mask:0xf bank_mask:0xf
	v_mov_b32_e32 v247, v16
	v_dot2c_f32_bf16_dpp v247, v0, v8 row_newbcast:11 row_mask:0xf bank_mask:0xf
	v_dot2c_f32_bf16_dpp v247, v1, v9 row_newbcast:11 row_mask:0xf bank_mask:0xf
	v_dot2c_f32_bf16_dpp v247, v2, v10 row_newbcast:11 row_mask:0xf bank_mask:0xf
	v_dot2c_f32_bf16_dpp v247, v3, v11 row_newbcast:11 row_mask:0xf bank_mask:0xf
	v_dot2c_f32_bf16_dpp v247, v4, v12 row_newbcast:11 row_mask:0xf bank_mask:0xf
	v_dot2c_f32_bf16_dpp v247, v5, v13 row_newbcast:11 row_mask:0xf bank_mask:0xf
	v_dot2c_f32_bf16_dpp v247, v6, v14 row_newbcast:11 row_mask:0xf bank_mask:0xf
	v_dot2c_f32_bf16_dpp v247, v7, v15 row_newbcast:11 row_mask:0xf bank_mask:0xf
	v_mov_b32_e32 v248, v16
	v_dot2c_f32_bf16_dpp v248, v0, v8 row_newbcast:12 row_mask:0xf bank_mask:0xf
	v_dot2c_f32_bf16_dpp v248, v1, v9 row_newbcast:12 row_mask:0xf bank_mask:0xf
	v_dot2c_f32_bf16_dpp v248, v2, v10 row_newbcast:12 row_mask:0xf bank_mask:0xf
	v_dot2c_f32_bf16_dpp v248, v3, v11 row_newbcast:12 row_mask:0xf bank_mask:0xf
	v_dot2c_f32_bf16_dpp v248, v4, v12 row_newbcast:12 row_mask:0xf bank_mask:0xf
	v_dot2c_f32_bf16_dpp v248, v5, v13 row_newbcast:12 row_mask:0xf bank_mask:0xf
	v_dot2c_f32_bf16_dpp v248, v6, v14 row_newbcast:12 row_mask:0xf bank_mask:0xf
	v_dot2c_f32_bf16_dpp v248, v7, v15 row_newbcast:12 row_mask:0xf bank_mask:0xf
	v_mov_b32_e32 v249, v16
	v_dot2c_f32_bf16_dpp v249, v0, v8 row_newbcast:13 row_mask:0xf bank_mask:0xf
	v_dot2c_f32_bf16_dpp v249, v1, v9 row_newbcast:13 row_mask:0xf bank_mask:0xf
	v_dot2c_f32_bf16_dpp v249, v2, v10 row_newbcast:13 row_mask:0xf bank_mask:0xf
	v_dot2c_f32_bf16_dpp v249, v3, v11 row_newbcast:13 row_mask:0xf bank_mask:0xf
	v_dot2c_f32_bf16_dpp v249, v4, v12 row_newbcast:13 row_mask:0xf bank_mask:0xf
	v_dot2c_f32_bf16_dpp v249, v5, v13 row_newbcast:13 row_mask:0xf bank_mask:0xf
	v_dot2c_f32_bf16_dpp v249, v6, v14 row_newbcast:13 row_mask:0xf bank_mask:0xf
	v_dot2c_f32_bf16_dpp v249, v7, v15 row_newbcast:13 row_mask:0xf bank_mask:0xf
	v_mov_b32_e32 v250, v16
	v_dot2c_f32_bf16_dpp v250, v0, v8 row_newbcast:14 row_mask:0xf bank_mask:0xf
	v_dot2c_f32_bf16_dpp v250, v1, v9 row_newbcast:14 row_mask:0xf bank_mask:0xf
	v_dot2c_f32_bf16_dpp v250, v2, v10 row_newbcast:14 row_mask:0xf bank_mask:0xf
	v_dot2c_f32_bf16_dpp v250, v3, v11 row_newbcast:14 row_mask:0xf bank_mask:0xf
	v_dot2c_f32_bf16_dpp v250, v4, v12 row_newbcast:14 row_mask:0xf bank_mask:0xf
	v_dot2c_f32_bf16_dpp v250, v5, v13 row_newbcast:14 row_mask:0xf bank_mask:0xf
	v_dot2c_f32_bf16_dpp v250, v6, v14 row_newbcast:14 row_mask:0xf bank_mask:0xf
	v_dot2c_f32_bf16_dpp v250, v7, v15 row_newbcast:14 row_mask:0xf bank_mask:0xf
	v_mov_b32_e32 v251, v16
	v_dot2c_f32_bf16_dpp v251, v0, v8 row_newbcast:15 row_mask:0xf bank_mask:0xf
	v_dot2c_f32_bf16_dpp v251, v1, v9 row_newbcast:15 row_mask:0xf bank_mask:0xf
	v_dot2c_f32_bf16_dpp v251, v2, v10 row_newbcast:15 row_mask:0xf bank_mask:0xf
	v_dot2c_f32_bf16_dpp v251, v3, v11 row_newbcast:15 row_mask:0xf bank_mask:0xf
	v_dot2c_f32_bf16_dpp v251, v4, v12 row_newbcast:15 row_mask:0xf bank_mask:0xf
	v_dot2c_f32_bf16_dpp v251, v5, v13 row_newbcast:15 row_mask:0xf bank_mask:0xf
	v_dot2c_f32_bf16_dpp v251, v6, v14 row_newbcast:15 row_mask:0xf bank_mask:0xf
	v_dot2c_f32_bf16_dpp v251, v7, v15 row_newbcast:15 row_mask:0xf bank_mask:0xf
	s_nop 2
	v_mul_f32_e64 v18, |v236|, s1
	v_mul_f32_e64 v19, |v237|, s1
	v_mul_f32_e64 v20, |v238|, s1
	v_mul_f32_e64 v21, |v239|, s1
	v_mul_f32_e64 v22, |v240|, s1
	v_mul_f32_e64 v23, |v241|, s1
	v_mul_f32_e64 v24, |v242|, s1
	v_mul_f32_e64 v25, |v243|, s1
	v_mul_f32_e64 v26, |v244|, s1
	v_mul_f32_e64 v27, |v245|, s1
	v_mul_f32_e64 v28, |v246|, s1
	v_mul_f32_e64 v29, |v247|, s1
	v_mul_f32_e64 v30, |v248|, s1
	v_mul_f32_e64 v31, |v249|, s1
	v_mul_f32_e64 v32, |v250|, s1
	v_mul_f32_e64 v33, |v251|, s1
	v_exp_f32_e32 v18, v18
	v_exp_f32_e32 v19, v19
	v_exp_f32_e32 v20, v20
	v_exp_f32_e32 v21, v21
	v_exp_f32_e32 v22, v22
	v_exp_f32_e32 v23, v23
	v_exp_f32_e32 v24, v24
	v_exp_f32_e32 v25, v25
	v_exp_f32_e32 v26, v26
	v_exp_f32_e32 v27, v27
	v_exp_f32_e32 v28, v28
	v_exp_f32_e32 v29, v29
	v_exp_f32_e32 v30, v30
	v_exp_f32_e32 v31, v31
	v_exp_f32_e32 v32, v32
	v_exp_f32_e32 v33, v33
	v_max_f32_e64 v236, -v236, 0
	v_max_f32_e64 v237, -v237, 0
	v_max_f32_e64 v238, -v238, 0
	v_max_f32_e64 v239, -v239, 0
	v_max_f32_e64 v240, -v240, 0
	v_max_f32_e64 v241, -v241, 0
	v_max_f32_e64 v242, -v242, 0
	v_max_f32_e64 v243, -v243, 0
	v_max_f32_e64 v244, -v244, 0
; __device__ __forceinline__ void gl1_item(PREF p, int l, int item, bool valid, LAS unsigned char* pl, int sw, int lane) {
;     ...
;             if (g4 < 3) {
; #pragma unroll
;                 for (int ss = 0; ss < 16; ++ss) { const int s = (g4 + 1) * 16 + ss; const int i = d ? 63 - s : s; const bf16_t* pr = P + (size_t)(row0 + i * rstride) * PW + h * 64 + lane;
;                     qn[ss] = __builtin_bit_cast(float, (unsigned)pr[1024]); kn[ss] = __builtin_bit_cast(float, (unsigned)pr[1280]); }
;                 __builtin_amdgcn_sched_barrier(0);
;             }
;             float gv[16];
; #pragma unroll
;             for (int ss = 0; ss < 16; ++ss) { const int s = g4 * 16 + ss; const int i = d ? 63 - s : s;
;                 float z = bup;
; #pragma unroll
;                 for (int r2 = 0; r2 < 8; ++r2) { const unsigned w = (unsigned)__builtin_amdgcn_readlane((int)lrp[r2], i);
;                     z = __builtin_amdgcn_fdot2_f32_bf16(__builtin_bit_cast(bf16x2_t, w), __builtin_bit_cast(bf16x2_t, wupp[r2]), z, false); }
;                 gv[ss] = -(fmaxf(-z, 0.f) + __logf(1.f + __expf(-fabsf(z)))) * (1.f / 16.f);
;                 __builtin_amdgcn_sched_barrier(0);
;             }
; #pragma unroll
;             for (int ss = 0; ss < 16; ++ss) { const int s = g4 * 16 + ss; const int i = d ? 63 - s : s; const size_t rowi = (size_t)(row0 + i * rstride);
;                 bc += gv[ss];
;                 const float en = __expf(-bc), ep = __expf(bc);
;                 const float kt = kc[ss] * en, qt = qc[ss] * 0.125f * ep;
	v_max_f32_e64 v245, -v245, 0
	v_max_f32_e64 v246, -v246, 0
	v_max_f32_e64 v247, -v247, 0
	v_max_f32_e64 v248, -v248, 0
	v_max_f32_e64 v249, -v249, 0
	v_max_f32_e64 v250, -v250, 0
	v_max_f32_e64 v251, -v251, 0
	v_add_f32_e32 v18, 1.0, v18
	v_add_f32_e32 v19, 1.0, v19
	v_add_f32_e32 v20, 1.0, v20
	v_add_f32_e32 v21, 1.0, v21
	v_add_f32_e32 v22, 1.0, v22
	v_add_f32_e32 v23, 1.0, v23
	v_add_f32_e32 v24, 1.0, v24
	v_add_f32_e32 v25, 1.0, v25
	v_add_f32_e32 v26, 1.0, v26
	v_add_f32_e32 v27, 1.0, v27
	v_add_f32_e32 v28, 1.0, v28
	v_add_f32_e32 v29, 1.0, v29
	v_add_f32_e32 v30, 1.0, v30
	v_add_f32_e32 v31, 1.0, v31
	v_add_f32_e32 v32, 1.0, v32
	v_add_f32_e32 v33, 1.0, v33
	v_log_f32_e32 v18, v18
	v_log_f32_e32 v19, v19
	v_log_f32_e32 v20, v20
	v_log_f32_e32 v21, v21
	v_log_f32_e32 v22, v22
	v_log_f32_e32 v23, v23
	v_log_f32_e32 v24, v24
	v_log_f32_e32 v25, v25
	v_log_f32_e32 v26, v26
	v_log_f32_e32 v27, v27
	v_log_f32_e32 v28, v28
	v_log_f32_e32 v29, v29
	v_log_f32_e32 v30, v30
	v_log_f32_e32 v31, v31
	v_log_f32_e32 v32, v32
	v_log_f32_e32 v33, v33
	v_fmac_f32_e32 v236, 0x3f317218, v18
	v_fmac_f32_e32 v237, 0x3f317218, v19
	v_fmac_f32_e32 v238, 0x3f317218, v20
	v_fmac_f32_e32 v239, 0x3f317218, v21
	v_fmac_f32_e32 v240, 0x3f317218, v22
	v_fmac_f32_e32 v241, 0x3f317218, v23
	v_fmac_f32_e32 v242, 0x3f317218, v24
	v_fmac_f32_e32 v243, 0x3f317218, v25
	v_fmac_f32_e32 v244, 0x3f317218, v26
	v_fmac_f32_e32 v245, 0x3f317218, v27
	v_fmac_f32_e32 v246, 0x3f317218, v28
	v_fmac_f32_e32 v247, 0x3f317218, v29
	v_fmac_f32_e32 v248, 0x3f317218, v30
	v_fmac_f32_e32 v249, 0x3f317218, v31
	v_fmac_f32_e32 v250, 0x3f317218, v32
	v_fmac_f32_e32 v251, 0x3f317218, v33
	v_fma_f32 v70, v236, s49, v17
	v_fma_f32 v71, v237, s49, v70
	v_fma_f32 v72, v238, s49, v71
	v_fma_f32 v73, v239, s49, v72
	v_fma_f32 v74, v240, s49, v73
	v_fma_f32 v75, v241, s49, v74
	v_fma_f32 v76, v242, s49, v75
	v_fma_f32 v77, v243, s49, v76
	v_fma_f32 v78, v244, s49, v77
	v_fma_f32 v79, v245, s49, v78
	v_fma_f32 v80, v246, s49, v79
	v_fma_f32 v81, v247, s49, v80
	v_fma_f32 v82, v248, s49, v81
	v_fma_f32 v83, v249, s49, v82
	v_fma_f32 v84, v250, s49, v83
	v_fma_f32 v85, v251, s49, v84
	v_mov_b32_e32 v17, v85
	s_waitcnt vmcnt(0)
	global_load_ushort v180, v134, s[6:7]
	global_load_ushort v196, v134, s[6:7] offset:512
	s_add_u32 s6, s6, s54
	s_addc_u32 s7, s7, s55
	global_load_ushort v181, v134, s[6:7]
	global_load_ushort v197, v134, s[6:7] offset:512
	s_add_u32 s6, s6, s54
	s_addc_u32 s7, s7, s55
	global_load_ushort v182, v134, s[6:7]
	global_load_ushort v198, v134, s[6:7] offset:512
	s_add_u32 s6, s6, s54
	s_addc_u32 s7, s7, s55
	global_load_ushort v183, v134, s[6:7]
	global_load_ushort v199, v134, s[6:7] offset:512
	s_add_u32 s6, s6, s54
	s_addc_u32 s7, s7, s55
	global_load_ushort v184, v134, s[6:7]
	global_load_ushort v200, v134, s[6:7] offset:512
	s_add_u32 s6, s6, s54
	s_addc_u32 s7, s7, s55
	global_load_ushort v185, v134, s[6:7]
	global_load_ushort v201, v134, s[6:7] offset:512
	s_add_u32 s6, s6, s54
	s_addc_u32 s7, s7, s55
	global_load_ushort v186, v134, s[6:7]
	global_load_ushort v202, v134, s[6:7] offset:512
	s_add_u32 s6, s6, s54
	s_addc_u32 s7, s7, s55
	global_load_ushort v187, v134, s[6:7]
	global_load_ushort v203, v134, s[6:7] offset:512
	s_add_u32 s6, s6, s54
	s_addc_u32 s7, s7, s55
	global_load_ushort v188, v134, s[6:7]
	global_load_ushort v204, v134, s[6:7] offset:512
	s_add_u32 s6, s6, s54
	s_addc_u32 s7, s7, s55
	global_load_ushort v189, v134, s[6:7]
	global_load_ushort v205, v134, s[6:7] offset:512
	s_add_u32 s6, s6, s54
	s_addc_u32 s7, s7, s55
	global_load_ushort v190, v134, s[6:7]
	global_load_ushort v206, v134, s[6:7] offset:512
	s_add_u32 s6, s6, s54
	s_addc_u32 s7, s7, s55
	global_load_ushort v191, v134, s[6:7]
	global_load_ushort v207, v134, s[6:7] offset:512
	s_add_u32 s6, s6, s54
	s_addc_u32 s7, s7, s55
	global_load_ushort v192, v134, s[6:7]
	global_load_ushort v208, v134, s[6:7] offset:512
	s_add_u32 s6, s6, s54
	s_addc_u32 s7, s7, s55
	global_load_ushort v193, v134, s[6:7]
	global_load_ushort v209, v134, s[6:7] offset:512
	s_add_u32 s6, s6, s54
	s_addc_u32 s7, s7, s55
	global_load_ushort v194, v134, s[6:7]
	global_load_ushort v210, v134, s[6:7] offset:512
	s_add_u32 s6, s6, s54
	s_addc_u32 s7, s7, s55
	global_load_ushort v195, v134, s[6:7]
	global_load_ushort v211, v134, s[6:7] offset:512
	s_add_u32 s6, s6, s54
	s_addc_u32 s7, s7, s55
	v_mul_f32_e32 v18, 0xbfb8aa3b, v70
	v_mul_f32_e32 v19, 0xbfb8aa3b, v71
	v_mul_f32_e32 v20, 0xbfb8aa3b, v72
	v_mul_f32_e32 v21, 0xbfb8aa3b, v73
	v_mul_f32_e32 v22, 0xbfb8aa3b, v74
	v_mul_f32_e32 v23, 0xbfb8aa3b, v75
	v_mul_f32_e32 v24, 0xbfb8aa3b, v76
	v_mul_f32_e32 v25, 0xbfb8aa3b, v77
	v_mul_f32_e32 v26, 0xbfb8aa3b, v78
	v_mul_f32_e32 v27, 0xbfb8aa3b, v79
	v_mul_f32_e32 v28, 0xbfb8aa3b, v80
	v_mul_f32_e32 v29, 0xbfb8aa3b, v81
	v_mul_f32_e32 v30, 0xbfb8aa3b, v82
	v_mul_f32_e32 v31, 0xbfb8aa3b, v83
	v_mul_f32_e32 v32, 0xbfb8aa3b, v84
	v_mul_f32_e32 v33, 0xbfb8aa3b, v85
	v_exp_f32_e64 v236, -v18
	v_exp_f32_e64 v237, -v19
	v_exp_f32_e64 v238, -v20
	v_exp_f32_e64 v239, -v21
	v_exp_f32_e64 v240, -v22
	v_exp_f32_e64 v241, -v23
	v_exp_f32_e64 v242, -v24
	v_exp_f32_e64 v243, -v25
	v_exp_f32_e64 v244, -v26
	v_exp_f32_e64 v245, -v27
	v_exp_f32_e64 v246, -v28
	v_exp_f32_e64 v247, -v29
	v_exp_f32_e64 v248, -v30
	v_exp_f32_e64 v249, -v31
	v_exp_f32_e64 v250, -v32
	v_exp_f32_e64 v251, -v33
	v_exp_f32_e32 v18, v18
	v_exp_f32_e32 v19, v19
	v_exp_f32_e32 v20, v20
	v_exp_f32_e32 v21, v21
	v_exp_f32_e32 v22, v22
	v_exp_f32_e32 v23, v23
	v_exp_f32_e32 v24, v24
	v_exp_f32_e32 v25, v25
	v_exp_f32_e32 v26, v26
	v_exp_f32_e32 v27, v27
	v_exp_f32_e32 v28, v28
; __device__ __forceinline__ unsigned f2bf(float f) { unsigned r; asm("v_cvt_pk_bf16_f32 %0, %1, %1" : "=v"(r) : "v"(f)); return r & 0xffffu; }
; __device__ __forceinline__ void gl1_item(PREF p, int l, int item, bool valid, LAS unsigned char* pl, int sw, int lane) {
;     ...
;             for (int ss = 0; ss < 16; ++ss) { const int s = g4 * 16 + ss; const int i = d ? 63 - s : s; const size_t rowi = (size_t)(row0 + i * rstride);
;                 bc += gv[ss];
;                 const float en = __expf(-bc), ep = __expf(bc);
;                 const float kt = kc[ss] * en, qt = qc[ss] * 0.125f * ep;
;                 const unsigned ktb = f2bf(kt);
;                 sKt[lane * 72 + i] = (bf16_t)ktb;
;                 QK[rowi * 1024 + d * 512 + h * 64 + lane] = (bf16_t)f2bf(qt);
;                 QK[rowi * 1024 + d * 512 + 256 + h * 64 + lane] = (bf16_t)ktb;
;             }
	v_exp_f32_e32 v29, v29
	v_exp_f32_e32 v30, v30
	v_exp_f32_e32 v31, v31
	v_exp_f32_e32 v32, v32
	v_exp_f32_e32 v33, v33
	v_lshlrev_b32_e32 v164, 16, v164
	v_lshlrev_b32_e32 v165, 16, v165
	v_lshlrev_b32_e32 v166, 16, v166
	v_lshlrev_b32_e32 v167, 16, v167
	v_lshlrev_b32_e32 v168, 16, v168
	v_lshlrev_b32_e32 v169, 16, v169
	v_lshlrev_b32_e32 v170, 16, v170
	v_lshlrev_b32_e32 v171, 16, v171
	v_lshlrev_b32_e32 v172, 16, v172
	v_lshlrev_b32_e32 v173, 16, v173
	v_lshlrev_b32_e32 v174, 16, v174
	v_lshlrev_b32_e32 v175, 16, v175
	v_lshlrev_b32_e32 v176, 16, v176
	v_lshlrev_b32_e32 v177, 16, v177
	v_lshlrev_b32_e32 v178, 16, v178
	v_lshlrev_b32_e32 v179, 16, v179
	v_lshlrev_b32_e32 v148, 16, v148
	v_lshlrev_b32_e32 v149, 16, v149
	v_lshlrev_b32_e32 v150, 16, v150
	v_lshlrev_b32_e32 v151, 16, v151
	v_lshlrev_b32_e32 v152, 16, v152
	v_lshlrev_b32_e32 v153, 16, v153
	v_lshlrev_b32_e32 v154, 16, v154
	v_lshlrev_b32_e32 v155, 16, v155
	v_lshlrev_b32_e32 v156, 16, v156
	v_lshlrev_b32_e32 v157, 16, v157
	v_lshlrev_b32_e32 v158, 16, v158
	v_lshlrev_b32_e32 v159, 16, v159
	v_lshlrev_b32_e32 v160, 16, v160
	v_lshlrev_b32_e32 v161, 16, v161
	v_lshlrev_b32_e32 v162, 16, v162
	v_lshlrev_b32_e32 v163, 16, v163
	v_mul_f32_e32 v18, v18, v164
	v_mul_f32_e32 v19, v19, v165
	v_mul_f32_e32 v20, v20, v166
	v_mul_f32_e32 v21, v21, v167
	v_mul_f32_e32 v22, v22, v168
	v_mul_f32_e32 v23, v23, v169
	v_mul_f32_e32 v24, v24, v170
	v_mul_f32_e32 v25, v25, v171
	v_mul_f32_e32 v26, v26, v172
	v_mul_f32_e32 v27, v27, v173
	v_mul_f32_e32 v28, v28, v174
	v_mul_f32_e32 v29, v29, v175
	v_mul_f32_e32 v30, v30, v176
	v_mul_f32_e32 v31, v31, v177
	v_mul_f32_e32 v32, v32, v178
	v_mul_f32_e32 v33, v33, v179
	v_mul_f32_e32 v70, 0x3e000000, v148
	v_mul_f32_e32 v71, 0x3e000000, v149
	v_mul_f32_e32 v72, 0x3e000000, v150
	v_mul_f32_e32 v73, 0x3e000000, v151
	v_mul_f32_e32 v74, 0x3e000000, v152
	v_mul_f32_e32 v75, 0x3e000000, v153
	v_mul_f32_e32 v76, 0x3e000000, v154
	v_mul_f32_e32 v77, 0x3e000000, v155
	v_mul_f32_e32 v78, 0x3e000000, v156
	v_mul_f32_e32 v79, 0x3e000000, v157
	v_mul_f32_e32 v80, 0x3e000000, v158
	v_mul_f32_e32 v81, 0x3e000000, v159
	v_mul_f32_e32 v82, 0x3e000000, v160
	v_mul_f32_e32 v83, 0x3e000000, v161
	v_mul_f32_e32 v84, 0x3e000000, v162
	v_mul_f32_e32 v85, 0x3e000000, v163
	v_mul_f32_e32 v236, v70, v236
	v_mul_f32_e32 v237, v71, v237
	v_mul_f32_e32 v238, v72, v238
	v_mul_f32_e32 v239, v73, v239
	v_mul_f32_e32 v240, v74, v240
	v_mul_f32_e32 v241, v75, v241
	v_mul_f32_e32 v242, v76, v242
	v_mul_f32_e32 v243, v77, v243
	v_mul_f32_e32 v244, v78, v244
	v_mul_f32_e32 v245, v79, v245
	v_mul_f32_e32 v246, v80, v246
	v_mul_f32_e32 v247, v81, v247
	v_mul_f32_e32 v248, v82, v248
	v_mul_f32_e32 v249, v83, v249
	v_mul_f32_e32 v250, v84, v250
	v_mul_f32_e32 v251, v85, v251
	v_cvt_pk_bf16_f32 v18, v18, v236
	v_cvt_pk_bf16_f32 v19, v19, v237
	v_cvt_pk_bf16_f32 v20, v20, v238
	v_cvt_pk_bf16_f32 v21, v21, v239
	v_cvt_pk_bf16_f32 v22, v22, v240
	v_cvt_pk_bf16_f32 v23, v23, v241
	v_cvt_pk_bf16_f32 v24, v24, v242
	v_cvt_pk_bf16_f32 v25, v25, v243
	v_cvt_pk_bf16_f32 v26, v26, v244
	v_cvt_pk_bf16_f32 v27, v27, v245
	v_cvt_pk_bf16_f32 v28, v28, v246
	v_cvt_pk_bf16_f32 v29, v29, v247
	v_cvt_pk_bf16_f32 v30, v30, v248
	v_cvt_pk_bf16_f32 v31, v31, v249
	v_cvt_pk_bf16_f32 v32, v32, v250
	v_cvt_pk_bf16_f32 v33, v33, v251
	ds_write_b16 v60, v18
	v_add_u32_e32 v60, v61, v60
	global_store_short_d16_hi v134, v18, s[4:5]
	global_store_short v134, v18, s[4:5] offset:512
	s_add_u32 s4, s4, s56
	s_addc_u32 s5, s5, s3
	ds_write_b16 v60, v19
	v_add_u32_e32 v60, v61, v60
	global_store_short_d16_hi v134, v19, s[4:5]
	global_store_short v134, v19, s[4:5] offset:512
	s_add_u32 s4, s4, s56
	s_addc_u32 s5, s5, s3
	ds_write_b16 v60, v20
	v_add_u32_e32 v60, v61, v60
	global_store_short_d16_hi v134, v20, s[4:5]
	global_store_short v134, v20, s[4:5] offset:512
	s_add_u32 s4, s4, s56
	s_addc_u32 s5, s5, s3
	ds_write_b16 v60, v21
	v_add_u32_e32 v60, v61, v60
	global_store_short_d16_hi v134, v21, s[4:5]
	global_store_short v134, v21, s[4:5] offset:512
	s_add_u32 s4, s4, s56
	s_addc_u32 s5, s5, s3
	ds_write_b16 v60, v22
	v_add_u32_e32 v60, v61, v60
	global_store_short_d16_hi v134, v22, s[4:5]
	global_store_short v134, v22, s[4:5] offset:512
	s_add_u32 s4, s4, s56
	s_addc_u32 s5, s5, s3
	ds_write_b16 v60, v23
	v_add_u32_e32 v60, v61, v60
	global_store_short_d16_hi v134, v23, s[4:5]
	global_store_short v134, v23, s[4:5] offset:512
	s_add_u32 s4, s4, s56
	s_addc_u32 s5, s5, s3
	ds_write_b16 v60, v24
	v_add_u32_e32 v60, v61, v60
	global_store_short_d16_hi v134, v24, s[4:5]
	global_store_short v134, v24, s[4:5] offset:512
	s_add_u32 s4, s4, s56
	s_addc_u32 s5, s5, s3
	ds_write_b16 v60, v25
	v_add_u32_e32 v60, v61, v60
	global_store_short_d16_hi v134, v25, s[4:5]
	global_store_short v134, v25, s[4:5] offset:512
	s_add_u32 s4, s4, s56
	s_addc_u32 s5, s5, s3
	ds_write_b16 v60, v26
	v_add_u32_e32 v60, v61, v60
	global_store_short_d16_hi v134, v26, s[4:5]
	global_store_short v134, v26, s[4:5] offset:512
	s_add_u32 s4, s4, s56
	s_addc_u32 s5, s5, s3
	ds_write_b16 v60, v27
	v_add_u32_e32 v60, v61, v60
	global_store_short_d16_hi v134, v27, s[4:5]
	global_store_short v134, v27, s[4:5] offset:512
	s_add_u32 s4, s4, s56
	s_addc_u32 s5, s5, s3
	ds_write_b16 v60, v28
	v_add_u32_e32 v60, v61, v60
	global_store_short_d16_hi v134, v28, s[4:5]
	global_store_short v134, v28, s[4:5] offset:512
	s_add_u32 s4, s4, s56
	s_addc_u32 s5, s5, s3
	ds_write_b16 v60, v29
	v_add_u32_e32 v60, v61, v60
	global_store_short_d16_hi v134, v29, s[4:5]
	global_store_short v134, v29, s[4:5] offset:512
	s_add_u32 s4, s4, s56
	s_addc_u32 s5, s5, s3
	ds_write_b16 v60, v30
; __device__ __forceinline__ unsigned f2bf(float f) { unsigned r; asm("v_cvt_pk_bf16_f32 %0, %1, %1" : "=v"(r) : "v"(f)); return r & 0xffffu; }
; __device__ __forceinline__ void gl1_item(PREF p, int l, int item, bool valid, LAS unsigned char* pl, int sw, int lane) {
;     ...
;             for (int ss = 0; ss < 16; ++ss) { const int s = g4 * 16 + ss; const int i = d ? 63 - s : s;
;                 float z = bup;
; #pragma unroll
;                 for (int r2 = 0; r2 < 8; ++r2) { const unsigned w = (unsigned)__builtin_amdgcn_readlane((int)lrp[r2], i);
;                     z = __builtin_amdgcn_fdot2_f32_bf16(__builtin_bit_cast(bf16x2_t, w), __builtin_bit_cast(bf16x2_t, wupp[r2]), z, false); }
;     ...
;             for (int ss = 0; ss < 16; ++ss) { const int s = g4 * 16 + ss; const int i = d ? 63 - s : s; const size_t rowi = (size_t)(row0 + i * rstride);
;                 bc += gv[ss];
;                 const float en = __expf(-bc), ep = __expf(bc);
;                 const float kt = kc[ss] * en, qt = qc[ss] * 0.125f * ep;
;                 const unsigned ktb = f2bf(kt);
;                 sKt[lane * 72 + i] = (bf16_t)ktb;
;                 QK[rowi * 1024 + d * 512 + h * 64 + lane] = (bf16_t)f2bf(qt);
;                 QK[rowi * 1024 + d * 512 + 256 + h * 64 + lane] = (bf16_t)ktb;
;             }
	v_add_u32_e32 v60, v61, v60
	global_store_short_d16_hi v134, v30, s[4:5]
	global_store_short v134, v30, s[4:5] offset:512
	s_add_u32 s4, s4, s56
	s_addc_u32 s5, s5, s3
	ds_write_b16 v60, v31
	v_add_u32_e32 v60, v61, v60
	global_store_short_d16_hi v134, v31, s[4:5]
	global_store_short v134, v31, s[4:5] offset:512
	s_add_u32 s4, s4, s56
	s_addc_u32 s5, s5, s3
	ds_write_b16 v60, v32
	v_add_u32_e32 v60, v61, v60
	global_store_short_d16_hi v134, v32, s[4:5]
	global_store_short v134, v32, s[4:5] offset:512
	s_add_u32 s4, s4, s56
	s_addc_u32 s5, s5, s3
	ds_write_b16 v60, v33
	v_add_u32_e32 v60, v61, v60
	global_store_short_d16_hi v134, v33, s[4:5]
	global_store_short v134, v33, s[4:5] offset:512
	s_add_u32 s4, s4, s56
	s_addc_u32 s5, s5, s3
	v_mov_b32_e32 v236, v16
	v_dot2c_f32_bf16_dpp v236, v106, v8 row_newbcast:0 row_mask:0xf bank_mask:0xf
	v_dot2c_f32_bf16_dpp v236, v107, v9 row_newbcast:0 row_mask:0xf bank_mask:0xf
	v_dot2c_f32_bf16_dpp v236, v108, v10 row_newbcast:0 row_mask:0xf bank_mask:0xf
	v_dot2c_f32_bf16_dpp v236, v109, v11 row_newbcast:0 row_mask:0xf bank_mask:0xf
	v_dot2c_f32_bf16_dpp v236, v110, v12 row_newbcast:0 row_mask:0xf bank_mask:0xf
	v_dot2c_f32_bf16_dpp v236, v111, v13 row_newbcast:0 row_mask:0xf bank_mask:0xf
	v_dot2c_f32_bf16_dpp v236, v112, v14 row_newbcast:0 row_mask:0xf bank_mask:0xf
	v_dot2c_f32_bf16_dpp v236, v113, v15 row_newbcast:0 row_mask:0xf bank_mask:0xf
	v_mov_b32_e32 v237, v16
	v_dot2c_f32_bf16_dpp v237, v106, v8 row_newbcast:1 row_mask:0xf bank_mask:0xf
	v_dot2c_f32_bf16_dpp v237, v107, v9 row_newbcast:1 row_mask:0xf bank_mask:0xf
	v_dot2c_f32_bf16_dpp v237, v108, v10 row_newbcast:1 row_mask:0xf bank_mask:0xf
	v_dot2c_f32_bf16_dpp v237, v109, v11 row_newbcast:1 row_mask:0xf bank_mask:0xf
	v_dot2c_f32_bf16_dpp v237, v110, v12 row_newbcast:1 row_mask:0xf bank_mask:0xf
	v_dot2c_f32_bf16_dpp v237, v111, v13 row_newbcast:1 row_mask:0xf bank_mask:0xf
	v_dot2c_f32_bf16_dpp v237, v112, v14 row_newbcast:1 row_mask:0xf bank_mask:0xf
	v_dot2c_f32_bf16_dpp v237, v113, v15 row_newbcast:1 row_mask:0xf bank_mask:0xf
	v_mov_b32_e32 v238, v16
	v_dot2c_f32_bf16_dpp v238, v106, v8 row_newbcast:2 row_mask:0xf bank_mask:0xf
	v_dot2c_f32_bf16_dpp v238, v107, v9 row_newbcast:2 row_mask:0xf bank_mask:0xf
	v_dot2c_f32_bf16_dpp v238, v108, v10 row_newbcast:2 row_mask:0xf bank_mask:0xf
	v_dot2c_f32_bf16_dpp v238, v109, v11 row_newbcast:2 row_mask:0xf bank_mask:0xf
	v_dot2c_f32_bf16_dpp v238, v110, v12 row_newbcast:2 row_mask:0xf bank_mask:0xf
	v_dot2c_f32_bf16_dpp v238, v111, v13 row_newbcast:2 row_mask:0xf bank_mask:0xf
	v_dot2c_f32_bf16_dpp v238, v112, v14 row_newbcast:2 row_mask:0xf bank_mask:0xf
	v_dot2c_f32_bf16_dpp v238, v113, v15 row_newbcast:2 row_mask:0xf bank_mask:0xf
	v_mov_b32_e32 v239, v16
	v_dot2c_f32_bf16_dpp v239, v106, v8 row_newbcast:3 row_mask:0xf bank_mask:0xf
	v_dot2c_f32_bf16_dpp v239, v107, v9 row_newbcast:3 row_mask:0xf bank_mask:0xf
	v_dot2c_f32_bf16_dpp v239, v108, v10 row_newbcast:3 row_mask:0xf bank_mask:0xf
	v_dot2c_f32_bf16_dpp v239, v109, v11 row_newbcast:3 row_mask:0xf bank_mask:0xf
	v_dot2c_f32_bf16_dpp v239, v110, v12 row_newbcast:3 row_mask:0xf bank_mask:0xf
	v_dot2c_f32_bf16_dpp v239, v111, v13 row_newbcast:3 row_mask:0xf bank_mask:0xf
	v_dot2c_f32_bf16_dpp v239, v112, v14 row_newbcast:3 row_mask:0xf bank_mask:0xf
	v_dot2c_f32_bf16_dpp v239, v113, v15 row_newbcast:3 row_mask:0xf bank_mask:0xf
	v_mov_b32_e32 v240, v16
	v_dot2c_f32_bf16_dpp v240, v106, v8 row_newbcast:4 row_mask:0xf bank_mask:0xf
	v_dot2c_f32_bf16_dpp v240, v107, v9 row_newbcast:4 row_mask:0xf bank_mask:0xf
	v_dot2c_f32_bf16_dpp v240, v108, v10 row_newbcast:4 row_mask:0xf bank_mask:0xf
	v_dot2c_f32_bf16_dpp v240, v109, v11 row_newbcast:4 row_mask:0xf bank_mask:0xf
	v_dot2c_f32_bf16_dpp v240, v110, v12 row_newbcast:4 row_mask:0xf bank_mask:0xf
	v_dot2c_f32_bf16_dpp v240, v111, v13 row_newbcast:4 row_mask:0xf bank_mask:0xf
	v_dot2c_f32_bf16_dpp v240, v112, v14 row_newbcast:4 row_mask:0xf bank_mask:0xf
	v_dot2c_f32_bf16_dpp v240, v113, v15 row_newbcast:4 row_mask:0xf bank_mask:0xf
	v_mov_b32_e32 v241, v16
	v_dot2c_f32_bf16_dpp v241, v106, v8 row_newbcast:5 row_mask:0xf bank_mask:0xf
	v_dot2c_f32_bf16_dpp v241, v107, v9 row_newbcast:5 row_mask:0xf bank_mask:0xf
	v_dot2c_f32_bf16_dpp v241, v108, v10 row_newbcast:5 row_mask:0xf bank_mask:0xf
	v_dot2c_f32_bf16_dpp v241, v109, v11 row_newbcast:5 row_mask:0xf bank_mask:0xf
	v_dot2c_f32_bf16_dpp v241, v110, v12 row_newbcast:5 row_mask:0xf bank_mask:0xf
	v_dot2c_f32_bf16_dpp v241, v111, v13 row_newbcast:5 row_mask:0xf bank_mask:0xf
	v_dot2c_f32_bf16_dpp v241, v112, v14 row_newbcast:5 row_mask:0xf bank_mask:0xf
	v_dot2c_f32_bf16_dpp v241, v113, v15 row_newbcast:5 row_mask:0xf bank_mask:0xf
	v_mov_b32_e32 v242, v16
	v_dot2c_f32_bf16_dpp v242, v106, v8 row_newbcast:6 row_mask:0xf bank_mask:0xf
	v_dot2c_f32_bf16_dpp v242, v107, v9 row_newbcast:6 row_mask:0xf bank_mask:0xf
	v_dot2c_f32_bf16_dpp v242, v108, v10 row_newbcast:6 row_mask:0xf bank_mask:0xf
	v_dot2c_f32_bf16_dpp v242, v109, v11 row_newbcast:6 row_mask:0xf bank_mask:0xf
	v_dot2c_f32_bf16_dpp v242, v110, v12 row_newbcast:6 row_mask:0xf bank_mask:0xf
	v_dot2c_f32_bf16_dpp v242, v111, v13 row_newbcast:6 row_mask:0xf bank_mask:0xf
	v_dot2c_f32_bf16_dpp v242, v112, v14 row_newbcast:6 row_mask:0xf bank_mask:0xf
	v_dot2c_f32_bf16_dpp v242, v113, v15 row_newbcast:6 row_mask:0xf bank_mask:0xf
	v_mov_b32_e32 v243, v16
	v_dot2c_f32_bf16_dpp v243, v106, v8 row_newbcast:7 row_mask:0xf bank_mask:0xf
	v_dot2c_f32_bf16_dpp v243, v107, v9 row_newbcast:7 row_mask:0xf bank_mask:0xf
	v_dot2c_f32_bf16_dpp v243, v108, v10 row_newbcast:7 row_mask:0xf bank_mask:0xf
; __device__ __forceinline__ void gl1_item(PREF p, int l, int item, bool valid, LAS unsigned char* pl, int sw, int lane) {
;     ...
;             for (int ss = 0; ss < 16; ++ss) { const int s = g4 * 16 + ss; const int i = d ? 63 - s : s;
;                 float z = bup;
; #pragma unroll
;                 for (int r2 = 0; r2 < 8; ++r2) { const unsigned w = (unsigned)__builtin_amdgcn_readlane((int)lrp[r2], i);
;                     z = __builtin_amdgcn_fdot2_f32_bf16(__builtin_bit_cast(bf16x2_t, w), __builtin_bit_cast(bf16x2_t, wupp[r2]), z, false); }
	v_dot2c_f32_bf16_dpp v243, v109, v11 row_newbcast:7 row_mask:0xf bank_mask:0xf
	v_dot2c_f32_bf16_dpp v243, v110, v12 row_newbcast:7 row_mask:0xf bank_mask:0xf
	v_dot2c_f32_bf16_dpp v243, v111, v13 row_newbcast:7 row_mask:0xf bank_mask:0xf
	v_dot2c_f32_bf16_dpp v243, v112, v14 row_newbcast:7 row_mask:0xf bank_mask:0xf
	v_dot2c_f32_bf16_dpp v243, v113, v15 row_newbcast:7 row_mask:0xf bank_mask:0xf
	v_mov_b32_e32 v244, v16
	v_dot2c_f32_bf16_dpp v244, v106, v8 row_newbcast:8 row_mask:0xf bank_mask:0xf
	v_dot2c_f32_bf16_dpp v244, v107, v9 row_newbcast:8 row_mask:0xf bank_mask:0xf
	v_dot2c_f32_bf16_dpp v244, v108, v10 row_newbcast:8 row_mask:0xf bank_mask:0xf
	v_dot2c_f32_bf16_dpp v244, v109, v11 row_newbcast:8 row_mask:0xf bank_mask:0xf
	v_dot2c_f32_bf16_dpp v244, v110, v12 row_newbcast:8 row_mask:0xf bank_mask:0xf
	v_dot2c_f32_bf16_dpp v244, v111, v13 row_newbcast:8 row_mask:0xf bank_mask:0xf
	v_dot2c_f32_bf16_dpp v244, v112, v14 row_newbcast:8 row_mask:0xf bank_mask:0xf
	v_dot2c_f32_bf16_dpp v244, v113, v15 row_newbcast:8 row_mask:0xf bank_mask:0xf
	v_mov_b32_e32 v245, v16
	v_dot2c_f32_bf16_dpp v245, v106, v8 row_newbcast:9 row_mask:0xf bank_mask:0xf
	v_dot2c_f32_bf16_dpp v245, v107, v9 row_newbcast:9 row_mask:0xf bank_mask:0xf
	v_dot2c_f32_bf16_dpp v245, v108, v10 row_newbcast:9 row_mask:0xf bank_mask:0xf
	v_dot2c_f32_bf16_dpp v245, v109, v11 row_newbcast:9 row_mask:0xf bank_mask:0xf
	v_dot2c_f32_bf16_dpp v245, v110, v12 row_newbcast:9 row_mask:0xf bank_mask:0xf
	v_dot2c_f32_bf16_dpp v245, v111, v13 row_newbcast:9 row_mask:0xf bank_mask:0xf
	v_dot2c_f32_bf16_dpp v245, v112, v14 row_newbcast:9 row_mask:0xf bank_mask:0xf
	v_dot2c_f32_bf16_dpp v245, v113, v15 row_newbcast:9 row_mask:0xf bank_mask:0xf
	v_mov_b32_e32 v246, v16
	v_dot2c_f32_bf16_dpp v246, v106, v8 row_newbcast:10 row_mask:0xf bank_mask:0xf
	v_dot2c_f32_bf16_dpp v246, v107, v9 row_newbcast:10 row_mask:0xf bank_mask:0xf
	v_dot2c_f32_bf16_dpp v246, v108, v10 row_newbcast:10 row_mask:0xf bank_mask:0xf
	v_dot2c_f32_bf16_dpp v246, v109, v11 row_newbcast:10 row_mask:0xf bank_mask:0xf
	v_dot2c_f32_bf16_dpp v246, v110, v12 row_newbcast:10 row_mask:0xf bank_mask:0xf
	v_dot2c_f32_bf16_dpp v246, v111, v13 row_newbcast:10 row_mask:0xf bank_mask:0xf
	v_dot2c_f32_bf16_dpp v246, v112, v14 row_newbcast:10 row_mask:0xf bank_mask:0xf
	v_dot2c_f32_bf16_dpp v246, v113, v15 row_newbcast:10 row_mask:0xf bank_mask:0xf
	v_mov_b32_e32 v247, v16
	v_dot2c_f32_bf16_dpp v247, v106, v8 row_newbcast:11 row_mask:0xf bank_mask:0xf
	v_dot2c_f32_bf16_dpp v247, v107, v9 row_newbcast:11 row_mask:0xf bank_mask:0xf
	v_dot2c_f32_bf16_dpp v247, v108, v10 row_newbcast:11 row_mask:0xf bank_mask:0xf
	v_dot2c_f32_bf16_dpp v247, v109, v11 row_newbcast:11 row_mask:0xf bank_mask:0xf
	v_dot2c_f32_bf16_dpp v247, v110, v12 row_newbcast:11 row_mask:0xf bank_mask:0xf
	v_dot2c_f32_bf16_dpp v247, v111, v13 row_newbcast:11 row_mask:0xf bank_mask:0xf
	v_dot2c_f32_bf16_dpp v247, v112, v14 row_newbcast:11 row_mask:0xf bank_mask:0xf
	v_dot2c_f32_bf16_dpp v247, v113, v15 row_newbcast:11 row_mask:0xf bank_mask:0xf
	v_mov_b32_e32 v248, v16
	v_dot2c_f32_bf16_dpp v248, v106, v8 row_newbcast:12 row_mask:0xf bank_mask:0xf
	v_dot2c_f32_bf16_dpp v248, v107, v9 row_newbcast:12 row_mask:0xf bank_mask:0xf
	v_dot2c_f32_bf16_dpp v248, v108, v10 row_newbcast:12 row_mask:0xf bank_mask:0xf
	v_dot2c_f32_bf16_dpp v248, v109, v11 row_newbcast:12 row_mask:0xf bank_mask:0xf
	v_dot2c_f32_bf16_dpp v248, v110, v12 row_newbcast:12 row_mask:0xf bank_mask:0xf
	v_dot2c_f32_bf16_dpp v248, v111, v13 row_newbcast:12 row_mask:0xf bank_mask:0xf
	v_dot2c_f32_bf16_dpp v248, v112, v14 row_newbcast:12 row_mask:0xf bank_mask:0xf
	v_dot2c_f32_bf16_dpp v248, v113, v15 row_newbcast:12 row_mask:0xf bank_mask:0xf
	v_mov_b32_e32 v249, v16
	v_dot2c_f32_bf16_dpp v249, v106, v8 row_newbcast:13 row_mask:0xf bank_mask:0xf
	v_dot2c_f32_bf16_dpp v249, v107, v9 row_newbcast:13 row_mask:0xf bank_mask:0xf
	v_dot2c_f32_bf16_dpp v249, v108, v10 row_newbcast:13 row_mask:0xf bank_mask:0xf
	v_dot2c_f32_bf16_dpp v249, v109, v11 row_newbcast:13 row_mask:0xf bank_mask:0xf
	v_dot2c_f32_bf16_dpp v249, v110, v12 row_newbcast:13 row_mask:0xf bank_mask:0xf
	v_dot2c_f32_bf16_dpp v249, v111, v13 row_newbcast:13 row_mask:0xf bank_mask:0xf
	v_dot2c_f32_bf16_dpp v249, v112, v14 row_newbcast:13 row_mask:0xf bank_mask:0xf
	v_dot2c_f32_bf16_dpp v249, v113, v15 row_newbcast:13 row_mask:0xf bank_mask:0xf
	v_mov_b32_e32 v250, v16
	v_dot2c_f32_bf16_dpp v250, v106, v8 row_newbcast:14 row_mask:0xf bank_mask:0xf
	v_dot2c_f32_bf16_dpp v250, v107, v9 row_newbcast:14 row_mask:0xf bank_mask:0xf
	v_dot2c_f32_bf16_dpp v250, v108, v10 row_newbcast:14 row_mask:0xf bank_mask:0xf
	v_dot2c_f32_bf16_dpp v250, v109, v11 row_newbcast:14 row_mask:0xf bank_mask:0xf
	v_dot2c_f32_bf16_dpp v250, v110, v12 row_newbcast:14 row_mask:0xf bank_mask:0xf
	v_dot2c_f32_bf16_dpp v250, v111, v13 row_newbcast:14 row_mask:0xf bank_mask:0xf
	v_dot2c_f32_bf16_dpp v250, v112, v14 row_newbcast:14 row_mask:0xf bank_mask:0xf
	v_dot2c_f32_bf16_dpp v250, v113, v15 row_newbcast:14 row_mask:0xf bank_mask:0xf
	v_mov_b32_e32 v251, v16
	v_dot2c_f32_bf16_dpp v251, v106, v8 row_newbcast:15 row_mask:0xf bank_mask:0xf
	v_dot2c_f32_bf16_dpp v251, v107, v9 row_newbcast:15 row_mask:0xf bank_mask:0xf
	v_dot2c_f32_bf16_dpp v251, v108, v10 row_newbcast:15 row_mask:0xf bank_mask:0xf
	v_dot2c_f32_bf16_dpp v251, v109, v11 row_newbcast:15 row_mask:0xf bank_mask:0xf
	v_dot2c_f32_bf16_dpp v251, v110, v12 row_newbcast:15 row_mask:0xf bank_mask:0xf
	v_dot2c_f32_bf16_dpp v251, v111, v13 row_newbcast:15 row_mask:0xf bank_mask:0xf
	v_dot2c_f32_bf16_dpp v251, v112, v14 row_newbcast:15 row_mask:0xf bank_mask:0xf
; __device__ __forceinline__ void gl1_item(PREF p, int l, int item, bool valid, LAS unsigned char* pl, int sw, int lane) {
;     ...
;             if (g4 < 3) {
; #pragma unroll
;                 for (int ss = 0; ss < 16; ++ss) { const int s = (g4 + 1) * 16 + ss; const int i = d ? 63 - s : s; const bf16_t* pr = P + (size_t)(row0 + i * rstride) * PW + h * 64 + lane;
;                     qn[ss] = __builtin_bit_cast(float, (unsigned)pr[1024]); kn[ss] = __builtin_bit_cast(float, (unsigned)pr[1280]); }
;                 __builtin_amdgcn_sched_barrier(0);
;             }
;     ...
;             for (int ss = 0; ss < 16; ++ss) { const int s = g4 * 16 + ss; const int i = d ? 63 - s : s;
;                 float z = bup;
; #pragma unroll
;                 for (int r2 = 0; r2 < 8; ++r2) { const unsigned w = (unsigned)__builtin_amdgcn_readlane((int)lrp[r2], i);
;                     z = __builtin_amdgcn_fdot2_f32_bf16(__builtin_bit_cast(bf16x2_t, w), __builtin_bit_cast(bf16x2_t, wupp[r2]), z, false); }
;                 gv[ss] = -(fmaxf(-z, 0.f) + __logf(1.f + __expf(-fabsf(z)))) * (1.f / 16.f);
;                 __builtin_amdgcn_sched_barrier(0);
;             }
; #pragma unroll
;             for (int ss = 0; ss < 16; ++ss) { const int s = g4 * 16 + ss; const int i = d ? 63 - s : s; const size_t rowi = (size_t)(row0 + i * rstride);
;                 bc += gv[ss];
;                 const float en = __expf(-bc), ep = __expf(bc);
;                 const float kt = kc[ss] * en, qt = qc[ss] * 0.125f * ep;
	v_dot2c_f32_bf16_dpp v251, v113, v15 row_newbcast:15 row_mask:0xf bank_mask:0xf
	s_nop 2
	v_mul_f32_e64 v18, |v236|, s1
	v_mul_f32_e64 v19, |v237|, s1
	v_mul_f32_e64 v20, |v238|, s1
	v_mul_f32_e64 v21, |v239|, s1
	v_mul_f32_e64 v22, |v240|, s1
	v_mul_f32_e64 v23, |v241|, s1
	v_mul_f32_e64 v24, |v242|, s1
	v_mul_f32_e64 v25, |v243|, s1
	v_mul_f32_e64 v26, |v244|, s1
	v_mul_f32_e64 v27, |v245|, s1
	v_mul_f32_e64 v28, |v246|, s1
	v_mul_f32_e64 v29, |v247|, s1
	v_mul_f32_e64 v30, |v248|, s1
	v_mul_f32_e64 v31, |v249|, s1
	v_mul_f32_e64 v32, |v250|, s1
	v_mul_f32_e64 v33, |v251|, s1
	v_exp_f32_e32 v18, v18
	v_exp_f32_e32 v19, v19
	v_exp_f32_e32 v20, v20
	v_exp_f32_e32 v21, v21
	v_exp_f32_e32 v22, v22
	v_exp_f32_e32 v23, v23
	v_exp_f32_e32 v24, v24
	v_exp_f32_e32 v25, v25
	v_exp_f32_e32 v26, v26
	v_exp_f32_e32 v27, v27
	v_exp_f32_e32 v28, v28
	v_exp_f32_e32 v29, v29
	v_exp_f32_e32 v30, v30
	v_exp_f32_e32 v31, v31
	v_exp_f32_e32 v32, v32
	v_exp_f32_e32 v33, v33
	v_max_f32_e64 v236, -v236, 0
	v_max_f32_e64 v237, -v237, 0
	v_max_f32_e64 v238, -v238, 0
	v_max_f32_e64 v239, -v239, 0
	v_max_f32_e64 v240, -v240, 0
	v_max_f32_e64 v241, -v241, 0
	v_max_f32_e64 v242, -v242, 0
	v_max_f32_e64 v243, -v243, 0
	v_max_f32_e64 v244, -v244, 0
	v_max_f32_e64 v245, -v245, 0
	v_max_f32_e64 v246, -v246, 0
	v_max_f32_e64 v247, -v247, 0
	v_max_f32_e64 v248, -v248, 0
	v_max_f32_e64 v249, -v249, 0
	v_max_f32_e64 v250, -v250, 0
	v_max_f32_e64 v251, -v251, 0
	v_add_f32_e32 v18, 1.0, v18
	v_add_f32_e32 v19, 1.0, v19
	v_add_f32_e32 v20, 1.0, v20
	v_add_f32_e32 v21, 1.0, v21
	v_add_f32_e32 v22, 1.0, v22
	v_add_f32_e32 v23, 1.0, v23
	v_add_f32_e32 v24, 1.0, v24
	v_add_f32_e32 v25, 1.0, v25
	v_add_f32_e32 v26, 1.0, v26
	v_add_f32_e32 v27, 1.0, v27
	v_add_f32_e32 v28, 1.0, v28
	v_add_f32_e32 v29, 1.0, v29
	v_add_f32_e32 v30, 1.0, v30
	v_add_f32_e32 v31, 1.0, v31
	v_add_f32_e32 v32, 1.0, v32
	v_add_f32_e32 v33, 1.0, v33
	v_log_f32_e32 v18, v18
	v_log_f32_e32 v19, v19
	v_log_f32_e32 v20, v20
	v_log_f32_e32 v21, v21
	v_log_f32_e32 v22, v22
	v_log_f32_e32 v23, v23
	v_log_f32_e32 v24, v24
	v_log_f32_e32 v25, v25
	v_log_f32_e32 v26, v26
	v_log_f32_e32 v27, v27
	v_log_f32_e32 v28, v28
	v_log_f32_e32 v29, v29
	v_log_f32_e32 v30, v30
	v_log_f32_e32 v31, v31
	v_log_f32_e32 v32, v32
	v_log_f32_e32 v33, v33
	v_fmac_f32_e32 v236, 0x3f317218, v18
	v_fmac_f32_e32 v237, 0x3f317218, v19
	v_fmac_f32_e32 v238, 0x3f317218, v20
	v_fmac_f32_e32 v239, 0x3f317218, v21
	v_fmac_f32_e32 v240, 0x3f317218, v22
	v_fmac_f32_e32 v241, 0x3f317218, v23
	v_fmac_f32_e32 v242, 0x3f317218, v24
	v_fmac_f32_e32 v243, 0x3f317218, v25
	v_fmac_f32_e32 v244, 0x3f317218, v26
	v_fmac_f32_e32 v245, 0x3f317218, v27
	v_fmac_f32_e32 v246, 0x3f317218, v28
	v_fmac_f32_e32 v247, 0x3f317218, v29
	v_fmac_f32_e32 v248, 0x3f317218, v30
	v_fmac_f32_e32 v249, 0x3f317218, v31
	v_fmac_f32_e32 v250, 0x3f317218, v32
	v_fmac_f32_e32 v251, 0x3f317218, v33
	v_fma_f32 v70, v236, s49, v17
	v_fma_f32 v71, v237, s49, v70
	v_fma_f32 v72, v238, s49, v71
	v_fma_f32 v73, v239, s49, v72
	v_fma_f32 v74, v240, s49, v73
	v_fma_f32 v75, v241, s49, v74
	v_fma_f32 v76, v242, s49, v75
	v_fma_f32 v77, v243, s49, v76
	v_fma_f32 v78, v244, s49, v77
	v_fma_f32 v79, v245, s49, v78
	v_fma_f32 v80, v246, s49, v79
	v_fma_f32 v81, v247, s49, v80
	v_fma_f32 v82, v248, s49, v81
	v_fma_f32 v83, v249, s49, v82
	v_fma_f32 v84, v250, s49, v83
	v_fma_f32 v85, v251, s49, v84
	v_mov_b32_e32 v17, v85
	s_waitcnt vmcnt(32)
	global_load_short_d16_hi v148, v134, s[6:7]
	global_load_short_d16_hi v164, v134, s[6:7] offset:512
	s_add_u32 s6, s6, s54
	s_addc_u32 s7, s7, s55
	global_load_short_d16_hi v149, v134, s[6:7]
	global_load_short_d16_hi v165, v134, s[6:7] offset:512
	s_add_u32 s6, s6, s54
	s_addc_u32 s7, s7, s55
	global_load_short_d16_hi v150, v134, s[6:7]
	global_load_short_d16_hi v166, v134, s[6:7] offset:512
	s_add_u32 s6, s6, s54
	s_addc_u32 s7, s7, s55
	global_load_short_d16_hi v151, v134, s[6:7]
	global_load_short_d16_hi v167, v134, s[6:7] offset:512
	s_add_u32 s6, s6, s54
	s_addc_u32 s7, s7, s55
	global_load_short_d16_hi v152, v134, s[6:7]
	global_load_short_d16_hi v168, v134, s[6:7] offset:512
	s_add_u32 s6, s6, s54
	s_addc_u32 s7, s7, s55
	global_load_short_d16_hi v153, v134, s[6:7]
	global_load_short_d16_hi v169, v134, s[6:7] offset:512
	s_add_u32 s6, s6, s54
	s_addc_u32 s7, s7, s55
	global_load_short_d16_hi v154, v134, s[6:7]
	global_load_short_d16_hi v170, v134, s[6:7] offset:512
	s_add_u32 s6, s6, s54
	s_addc_u32 s7, s7, s55
	global_load_short_d16_hi v155, v134, s[6:7]
	global_load_short_d16_hi v171, v134, s[6:7] offset:512
	s_add_u32 s6, s6, s54
	s_addc_u32 s7, s7, s55
	global_load_short_d16_hi v156, v134, s[6:7]
	global_load_short_d16_hi v172, v134, s[6:7] offset:512
	s_add_u32 s6, s6, s54
	s_addc_u32 s7, s7, s55
	global_load_short_d16_hi v157, v134, s[6:7]
	global_load_short_d16_hi v173, v134, s[6:7] offset:512
	s_add_u32 s6, s6, s54
	s_addc_u32 s7, s7, s55
	global_load_short_d16_hi v158, v134, s[6:7]
	global_load_short_d16_hi v174, v134, s[6:7] offset:512
	s_add_u32 s6, s6, s54
	s_addc_u32 s7, s7, s55
	global_load_short_d16_hi v159, v134, s[6:7]
	global_load_short_d16_hi v175, v134, s[6:7] offset:512
	s_add_u32 s6, s6, s54
	s_addc_u32 s7, s7, s55
	global_load_short_d16_hi v160, v134, s[6:7]
	global_load_short_d16_hi v176, v134, s[6:7] offset:512
	s_add_u32 s6, s6, s54
	s_addc_u32 s7, s7, s55
	global_load_short_d16_hi v161, v134, s[6:7]
	global_load_short_d16_hi v177, v134, s[6:7] offset:512
	s_add_u32 s6, s6, s54
	s_addc_u32 s7, s7, s55
	global_load_short_d16_hi v162, v134, s[6:7]
	global_load_short_d16_hi v178, v134, s[6:7] offset:512
	s_add_u32 s6, s6, s54
; __device__ __forceinline__ unsigned f2bf(float f) { unsigned r; asm("v_cvt_pk_bf16_f32 %0, %1, %1" : "=v"(r) : "v"(f)); return r & 0xffffu; }
; __device__ __forceinline__ void gl1_item(PREF p, int l, int item, bool valid, LAS unsigned char* pl, int sw, int lane) {
;     ...
;             for (int ss = 0; ss < 16; ++ss) { const int s = g4 * 16 + ss; const int i = d ? 63 - s : s; const size_t rowi = (size_t)(row0 + i * rstride);
;                 bc += gv[ss];
;                 const float en = __expf(-bc), ep = __expf(bc);
;                 const float kt = kc[ss] * en, qt = qc[ss] * 0.125f * ep;
;                 const unsigned ktb = f2bf(kt);
;                 sKt[lane * 72 + i] = (bf16_t)ktb;
;                 QK[rowi * 1024 + d * 512 + h * 64 + lane] = (bf16_t)f2bf(qt);
;                 QK[rowi * 1024 + d * 512 + 256 + h * 64 + lane] = (bf16_t)ktb;
;             }
; #pragma unroll
;             for (int ss = 0; ss < 16; ++ss) { qc[ss] = bf2f(__builtin_bit_cast(unsigned, qn[ss])); kc[ss] = bf2f(__builtin_bit_cast(unsigned, kn[ss])); }
	s_addc_u32 s7, s7, s55
	global_load_short_d16_hi v163, v134, s[6:7]
	global_load_short_d16_hi v179, v134, s[6:7] offset:512
	s_add_u32 s6, s6, s54
	s_addc_u32 s7, s7, s55
	v_mul_f32_e32 v18, 0xbfb8aa3b, v70
	v_mul_f32_e32 v19, 0xbfb8aa3b, v71
	v_mul_f32_e32 v20, 0xbfb8aa3b, v72
	v_mul_f32_e32 v21, 0xbfb8aa3b, v73
	v_mul_f32_e32 v22, 0xbfb8aa3b, v74
	v_mul_f32_e32 v23, 0xbfb8aa3b, v75
	v_mul_f32_e32 v24, 0xbfb8aa3b, v76
	v_mul_f32_e32 v25, 0xbfb8aa3b, v77
	v_mul_f32_e32 v26, 0xbfb8aa3b, v78
	v_mul_f32_e32 v27, 0xbfb8aa3b, v79
	v_mul_f32_e32 v28, 0xbfb8aa3b, v80
	v_mul_f32_e32 v29, 0xbfb8aa3b, v81
	v_mul_f32_e32 v30, 0xbfb8aa3b, v82
	v_mul_f32_e32 v31, 0xbfb8aa3b, v83
	v_mul_f32_e32 v32, 0xbfb8aa3b, v84
	v_mul_f32_e32 v33, 0xbfb8aa3b, v85
	v_exp_f32_e64 v236, -v18
	v_exp_f32_e64 v237, -v19
	v_exp_f32_e64 v238, -v20
	v_exp_f32_e64 v239, -v21
	v_exp_f32_e64 v240, -v22
	v_exp_f32_e64 v241, -v23
	v_exp_f32_e64 v242, -v24
	v_exp_f32_e64 v243, -v25
	v_exp_f32_e64 v244, -v26
	v_exp_f32_e64 v245, -v27
	v_exp_f32_e64 v246, -v28
	v_exp_f32_e64 v247, -v29
	v_exp_f32_e64 v248, -v30
	v_exp_f32_e64 v249, -v31
	v_exp_f32_e64 v250, -v32
	v_exp_f32_e64 v251, -v33
	v_exp_f32_e32 v18, v18
	v_exp_f32_e32 v19, v19
	v_exp_f32_e32 v20, v20
	v_exp_f32_e32 v21, v21
	v_exp_f32_e32 v22, v22
	v_exp_f32_e32 v23, v23
	v_exp_f32_e32 v24, v24
	v_exp_f32_e32 v25, v25
	v_exp_f32_e32 v26, v26
	v_exp_f32_e32 v27, v27
	v_exp_f32_e32 v28, v28
	v_exp_f32_e32 v29, v29
	v_exp_f32_e32 v30, v30
	v_exp_f32_e32 v31, v31
	v_exp_f32_e32 v32, v32
	v_exp_f32_e32 v33, v33
	v_lshlrev_b32_e32 v196, 16, v196
	v_lshlrev_b32_e32 v197, 16, v197
	v_lshlrev_b32_e32 v198, 16, v198
	v_lshlrev_b32_e32 v199, 16, v199
	v_lshlrev_b32_e32 v200, 16, v200
	v_lshlrev_b32_e32 v201, 16, v201
	v_lshlrev_b32_e32 v202, 16, v202
	v_lshlrev_b32_e32 v203, 16, v203
	v_lshlrev_b32_e32 v204, 16, v204
	v_lshlrev_b32_e32 v205, 16, v205
	v_lshlrev_b32_e32 v206, 16, v206
	v_lshlrev_b32_e32 v207, 16, v207
	v_lshlrev_b32_e32 v208, 16, v208
	v_lshlrev_b32_e32 v209, 16, v209
	v_lshlrev_b32_e32 v210, 16, v210
	v_lshlrev_b32_e32 v211, 16, v211
	v_lshlrev_b32_e32 v180, 16, v180
	v_lshlrev_b32_e32 v181, 16, v181
	v_lshlrev_b32_e32 v182, 16, v182
	v_lshlrev_b32_e32 v183, 16, v183
	v_lshlrev_b32_e32 v184, 16, v184
	v_lshlrev_b32_e32 v185, 16, v185
	v_lshlrev_b32_e32 v186, 16, v186
	v_lshlrev_b32_e32 v187, 16, v187
	v_lshlrev_b32_e32 v188, 16, v188
	v_lshlrev_b32_e32 v189, 16, v189
	v_lshlrev_b32_e32 v190, 16, v190
	v_lshlrev_b32_e32 v191, 16, v191
	v_lshlrev_b32_e32 v192, 16, v192
	v_lshlrev_b32_e32 v193, 16, v193
	v_lshlrev_b32_e32 v194, 16, v194
	v_lshlrev_b32_e32 v195, 16, v195
	v_mul_f32_e32 v18, v18, v196
	v_mul_f32_e32 v19, v19, v197
	v_mul_f32_e32 v20, v20, v198
	v_mul_f32_e32 v21, v21, v199
	v_mul_f32_e32 v22, v22, v200
	v_mul_f32_e32 v23, v23, v201
	v_mul_f32_e32 v24, v24, v202
	v_mul_f32_e32 v25, v25, v203
	v_mul_f32_e32 v26, v26, v204
	v_mul_f32_e32 v27, v27, v205
	v_mul_f32_e32 v28, v28, v206
	v_mul_f32_e32 v29, v29, v207
	v_mul_f32_e32 v30, v30, v208
	v_mul_f32_e32 v31, v31, v209
	v_mul_f32_e32 v32, v32, v210
	v_mul_f32_e32 v33, v33, v211
	v_mul_f32_e32 v70, 0x3e000000, v180
	v_mul_f32_e32 v71, 0x3e000000, v181
	v_mul_f32_e32 v72, 0x3e000000, v182
	v_mul_f32_e32 v73, 0x3e000000, v183
	v_mul_f32_e32 v74, 0x3e000000, v184
	v_mul_f32_e32 v75, 0x3e000000, v185
	v_mul_f32_e32 v76, 0x3e000000, v186
	v_mul_f32_e32 v77, 0x3e000000, v187
	v_mul_f32_e32 v78, 0x3e000000, v188
	v_mul_f32_e32 v79, 0x3e000000, v189
	v_mul_f32_e32 v80, 0x3e000000, v190
	v_mul_f32_e32 v81, 0x3e000000, v191
	v_mul_f32_e32 v82, 0x3e000000, v192
	v_mul_f32_e32 v83, 0x3e000000, v193
	v_mul_f32_e32 v84, 0x3e000000, v194
	v_mul_f32_e32 v85, 0x3e000000, v195
	v_mul_f32_e32 v236, v70, v236
	v_mul_f32_e32 v237, v71, v237
	v_mul_f32_e32 v238, v72, v238
	v_mul_f32_e32 v239, v73, v239
	v_mul_f32_e32 v240, v74, v240
	v_mul_f32_e32 v241, v75, v241
	v_mul_f32_e32 v242, v76, v242
	v_mul_f32_e32 v243, v77, v243
	v_mul_f32_e32 v244, v78, v244
	v_mul_f32_e32 v245, v79, v245
	v_mul_f32_e32 v246, v80, v246
	v_mul_f32_e32 v247, v81, v247
	v_mul_f32_e32 v248, v82, v248
	v_mul_f32_e32 v249, v83, v249
	v_mul_f32_e32 v250, v84, v250
	v_mul_f32_e32 v251, v85, v251
	v_cvt_pk_bf16_f32 v18, v18, v236
	v_cvt_pk_bf16_f32 v19, v19, v237
	v_cvt_pk_bf16_f32 v20, v20, v238
	v_cvt_pk_bf16_f32 v21, v21, v239
	v_cvt_pk_bf16_f32 v22, v22, v240
	v_cvt_pk_bf16_f32 v23, v23, v241
	v_cvt_pk_bf16_f32 v24, v24, v242
	v_cvt_pk_bf16_f32 v25, v25, v243
	v_cvt_pk_bf16_f32 v26, v26, v244
	v_cvt_pk_bf16_f32 v27, v27, v245
	v_cvt_pk_bf16_f32 v28, v28, v246
	v_cvt_pk_bf16_f32 v29, v29, v247
	v_cvt_pk_bf16_f32 v30, v30, v248
	v_cvt_pk_bf16_f32 v31, v31, v249
	v_cvt_pk_bf16_f32 v32, v32, v250
	v_cvt_pk_bf16_f32 v33, v33, v251
	ds_write_b16 v60, v18
	v_add_u32_e32 v60, v61, v60
	global_store_short_d16_hi v134, v18, s[4:5]
	global_store_short v134, v18, s[4:5] offset:512
	s_add_u32 s4, s4, s56
	s_addc_u32 s5, s5, s3
	ds_write_b16 v60, v19
	v_add_u32_e32 v60, v61, v60
	global_store_short_d16_hi v134, v19, s[4:5]
	global_store_short v134, v19, s[4:5] offset:512
	s_add_u32 s4, s4, s56
	s_addc_u32 s5, s5, s3
	ds_write_b16 v60, v20
	v_add_u32_e32 v60, v61, v60
	global_store_short_d16_hi v134, v20, s[4:5]
	global_store_short v134, v20, s[4:5] offset:512
	s_add_u32 s4, s4, s56
	s_addc_u32 s5, s5, s3
	ds_write_b16 v60, v21
	v_add_u32_e32 v60, v61, v60
	global_store_short_d16_hi v134, v21, s[4:5]
	global_store_short v134, v21, s[4:5] offset:512
	s_add_u32 s4, s4, s56
	s_addc_u32 s5, s5, s3
	ds_write_b16 v60, v22
	v_add_u32_e32 v60, v61, v60
	global_store_short_d16_hi v134, v22, s[4:5]
	global_store_short v134, v22, s[4:5] offset:512
; __device__ __forceinline__ unsigned f2bf(float f) { unsigned r; asm("v_cvt_pk_bf16_f32 %0, %1, %1" : "=v"(r) : "v"(f)); return r & 0xffffu; }
; __device__ __forceinline__ void gl1_item(PREF p, int l, int item, bool valid, LAS unsigned char* pl, int sw, int lane) {
;     ...
;             for (int ss = 0; ss < 16; ++ss) { const int s = g4 * 16 + ss; const int i = d ? 63 - s : s;
;                 float z = bup;
; #pragma unroll
;                 for (int r2 = 0; r2 < 8; ++r2) { const unsigned w = (unsigned)__builtin_amdgcn_readlane((int)lrp[r2], i);
;                     z = __builtin_amdgcn_fdot2_f32_bf16(__builtin_bit_cast(bf16x2_t, w), __builtin_bit_cast(bf16x2_t, wupp[r2]), z, false); }
;     ...
;             for (int ss = 0; ss < 16; ++ss) { const int s = g4 * 16 + ss; const int i = d ? 63 - s : s; const size_t rowi = (size_t)(row0 + i * rstride);
;                 bc += gv[ss];
;                 const float en = __expf(-bc), ep = __expf(bc);
;                 const float kt = kc[ss] * en, qt = qc[ss] * 0.125f * ep;
;                 const unsigned ktb = f2bf(kt);
;                 sKt[lane * 72 + i] = (bf16_t)ktb;
;                 QK[rowi * 1024 + d * 512 + h * 64 + lane] = (bf16_t)f2bf(qt);
;                 QK[rowi * 1024 + d * 512 + 256 + h * 64 + lane] = (bf16_t)ktb;
;             }
	s_add_u32 s4, s4, s56
	s_addc_u32 s5, s5, s3
	ds_write_b16 v60, v23
	v_add_u32_e32 v60, v61, v60
	global_store_short_d16_hi v134, v23, s[4:5]
	global_store_short v134, v23, s[4:5] offset:512
	s_add_u32 s4, s4, s56
	s_addc_u32 s5, s5, s3
	ds_write_b16 v60, v24
	v_add_u32_e32 v60, v61, v60
	global_store_short_d16_hi v134, v24, s[4:5]
	global_store_short v134, v24, s[4:5] offset:512
	s_add_u32 s4, s4, s56
	s_addc_u32 s5, s5, s3
	ds_write_b16 v60, v25
	v_add_u32_e32 v60, v61, v60
	global_store_short_d16_hi v134, v25, s[4:5]
	global_store_short v134, v25, s[4:5] offset:512
	s_add_u32 s4, s4, s56
	s_addc_u32 s5, s5, s3
	ds_write_b16 v60, v26
	v_add_u32_e32 v60, v61, v60
	global_store_short_d16_hi v134, v26, s[4:5]
	global_store_short v134, v26, s[4:5] offset:512
	s_add_u32 s4, s4, s56
	s_addc_u32 s5, s5, s3
	ds_write_b16 v60, v27
	v_add_u32_e32 v60, v61, v60
	global_store_short_d16_hi v134, v27, s[4:5]
	global_store_short v134, v27, s[4:5] offset:512
	s_add_u32 s4, s4, s56
	s_addc_u32 s5, s5, s3
	ds_write_b16 v60, v28
	v_add_u32_e32 v60, v61, v60
	global_store_short_d16_hi v134, v28, s[4:5]
	global_store_short v134, v28, s[4:5] offset:512
	s_add_u32 s4, s4, s56
	s_addc_u32 s5, s5, s3
	ds_write_b16 v60, v29
	v_add_u32_e32 v60, v61, v60
	global_store_short_d16_hi v134, v29, s[4:5]
	global_store_short v134, v29, s[4:5] offset:512
	s_add_u32 s4, s4, s56
	s_addc_u32 s5, s5, s3
	ds_write_b16 v60, v30
	v_add_u32_e32 v60, v61, v60
	global_store_short_d16_hi v134, v30, s[4:5]
	global_store_short v134, v30, s[4:5] offset:512
	s_add_u32 s4, s4, s56
	s_addc_u32 s5, s5, s3
	ds_write_b16 v60, v31
	v_add_u32_e32 v60, v61, v60
	global_store_short_d16_hi v134, v31, s[4:5]
	global_store_short v134, v31, s[4:5] offset:512
	s_add_u32 s4, s4, s56
	s_addc_u32 s5, s5, s3
	ds_write_b16 v60, v32
	v_add_u32_e32 v60, v61, v60
	global_store_short_d16_hi v134, v32, s[4:5]
	global_store_short v134, v32, s[4:5] offset:512
	s_add_u32 s4, s4, s56
	s_addc_u32 s5, s5, s3
	ds_write_b16 v60, v33
	v_add_u32_e32 v60, v61, v60
	global_store_short_d16_hi v134, v33, s[4:5]
	global_store_short v134, v33, s[4:5] offset:512
	s_add_u32 s4, s4, s56
	s_addc_u32 s5, s5, s3
	v_mov_b32_e32 v236, v16
	v_dot2c_f32_bf16_dpp v236, v114, v8 row_newbcast:0 row_mask:0xf bank_mask:0xf
	v_dot2c_f32_bf16_dpp v236, v115, v9 row_newbcast:0 row_mask:0xf bank_mask:0xf
	v_dot2c_f32_bf16_dpp v236, v116, v10 row_newbcast:0 row_mask:0xf bank_mask:0xf
	v_dot2c_f32_bf16_dpp v236, v117, v11 row_newbcast:0 row_mask:0xf bank_mask:0xf
	v_dot2c_f32_bf16_dpp v236, v118, v12 row_newbcast:0 row_mask:0xf bank_mask:0xf
	v_dot2c_f32_bf16_dpp v236, v119, v13 row_newbcast:0 row_mask:0xf bank_mask:0xf
	v_dot2c_f32_bf16_dpp v236, v120, v14 row_newbcast:0 row_mask:0xf bank_mask:0xf
	v_dot2c_f32_bf16_dpp v236, v121, v15 row_newbcast:0 row_mask:0xf bank_mask:0xf
	v_mov_b32_e32 v237, v16
	v_dot2c_f32_bf16_dpp v237, v114, v8 row_newbcast:1 row_mask:0xf bank_mask:0xf
	v_dot2c_f32_bf16_dpp v237, v115, v9 row_newbcast:1 row_mask:0xf bank_mask:0xf
	v_dot2c_f32_bf16_dpp v237, v116, v10 row_newbcast:1 row_mask:0xf bank_mask:0xf
	v_dot2c_f32_bf16_dpp v237, v117, v11 row_newbcast:1 row_mask:0xf bank_mask:0xf
	v_dot2c_f32_bf16_dpp v237, v118, v12 row_newbcast:1 row_mask:0xf bank_mask:0xf
	v_dot2c_f32_bf16_dpp v237, v119, v13 row_newbcast:1 row_mask:0xf bank_mask:0xf
	v_dot2c_f32_bf16_dpp v237, v120, v14 row_newbcast:1 row_mask:0xf bank_mask:0xf
	v_dot2c_f32_bf16_dpp v237, v121, v15 row_newbcast:1 row_mask:0xf bank_mask:0xf
	v_mov_b32_e32 v238, v16
	v_dot2c_f32_bf16_dpp v238, v114, v8 row_newbcast:2 row_mask:0xf bank_mask:0xf
	v_dot2c_f32_bf16_dpp v238, v115, v9 row_newbcast:2 row_mask:0xf bank_mask:0xf
	v_dot2c_f32_bf16_dpp v238, v116, v10 row_newbcast:2 row_mask:0xf bank_mask:0xf
	v_dot2c_f32_bf16_dpp v238, v117, v11 row_newbcast:2 row_mask:0xf bank_mask:0xf
	v_dot2c_f32_bf16_dpp v238, v118, v12 row_newbcast:2 row_mask:0xf bank_mask:0xf
	v_dot2c_f32_bf16_dpp v238, v119, v13 row_newbcast:2 row_mask:0xf bank_mask:0xf
	v_dot2c_f32_bf16_dpp v238, v120, v14 row_newbcast:2 row_mask:0xf bank_mask:0xf
	v_dot2c_f32_bf16_dpp v238, v121, v15 row_newbcast:2 row_mask:0xf bank_mask:0xf
	v_mov_b32_e32 v239, v16
	v_dot2c_f32_bf16_dpp v239, v114, v8 row_newbcast:3 row_mask:0xf bank_mask:0xf
	v_dot2c_f32_bf16_dpp v239, v115, v9 row_newbcast:3 row_mask:0xf bank_mask:0xf
	v_dot2c_f32_bf16_dpp v239, v116, v10 row_newbcast:3 row_mask:0xf bank_mask:0xf
	v_dot2c_f32_bf16_dpp v239, v117, v11 row_newbcast:3 row_mask:0xf bank_mask:0xf
	v_dot2c_f32_bf16_dpp v239, v118, v12 row_newbcast:3 row_mask:0xf bank_mask:0xf
	v_dot2c_f32_bf16_dpp v239, v119, v13 row_newbcast:3 row_mask:0xf bank_mask:0xf
	v_dot2c_f32_bf16_dpp v239, v120, v14 row_newbcast:3 row_mask:0xf bank_mask:0xf
	v_dot2c_f32_bf16_dpp v239, v121, v15 row_newbcast:3 row_mask:0xf bank_mask:0xf
	v_mov_b32_e32 v240, v16
	v_dot2c_f32_bf16_dpp v240, v114, v8 row_newbcast:4 row_mask:0xf bank_mask:0xf
	v_dot2c_f32_bf16_dpp v240, v115, v9 row_newbcast:4 row_mask:0xf bank_mask:0xf
	v_dot2c_f32_bf16_dpp v240, v116, v10 row_newbcast:4 row_mask:0xf bank_mask:0xf
	v_dot2c_f32_bf16_dpp v240, v117, v11 row_newbcast:4 row_mask:0xf bank_mask:0xf
	v_dot2c_f32_bf16_dpp v240, v118, v12 row_newbcast:4 row_mask:0xf bank_mask:0xf
	v_dot2c_f32_bf16_dpp v240, v119, v13 row_newbcast:4 row_mask:0xf bank_mask:0xf
	v_dot2c_f32_bf16_dpp v240, v120, v14 row_newbcast:4 row_mask:0xf bank_mask:0xf
	v_dot2c_f32_bf16_dpp v240, v121, v15 row_newbcast:4 row_mask:0xf bank_mask:0xf
	v_mov_b32_e32 v241, v16
	v_dot2c_f32_bf16_dpp v241, v114, v8 row_newbcast:5 row_mask:0xf bank_mask:0xf
	v_dot2c_f32_bf16_dpp v241, v115, v9 row_newbcast:5 row_mask:0xf bank_mask:0xf
; __device__ __forceinline__ void gl1_item(PREF p, int l, int item, bool valid, LAS unsigned char* pl, int sw, int lane) {
;     ...
;             for (int ss = 0; ss < 16; ++ss) { const int s = g4 * 16 + ss; const int i = d ? 63 - s : s;
;                 float z = bup;
; #pragma unroll
;                 for (int r2 = 0; r2 < 8; ++r2) { const unsigned w = (unsigned)__builtin_amdgcn_readlane((int)lrp[r2], i);
;                     z = __builtin_amdgcn_fdot2_f32_bf16(__builtin_bit_cast(bf16x2_t, w), __builtin_bit_cast(bf16x2_t, wupp[r2]), z, false); }
	v_dot2c_f32_bf16_dpp v241, v116, v10 row_newbcast:5 row_mask:0xf bank_mask:0xf
	v_dot2c_f32_bf16_dpp v241, v117, v11 row_newbcast:5 row_mask:0xf bank_mask:0xf
	v_dot2c_f32_bf16_dpp v241, v118, v12 row_newbcast:5 row_mask:0xf bank_mask:0xf
	v_dot2c_f32_bf16_dpp v241, v119, v13 row_newbcast:5 row_mask:0xf bank_mask:0xf
	v_dot2c_f32_bf16_dpp v241, v120, v14 row_newbcast:5 row_mask:0xf bank_mask:0xf
	v_dot2c_f32_bf16_dpp v241, v121, v15 row_newbcast:5 row_mask:0xf bank_mask:0xf
	v_mov_b32_e32 v242, v16
	v_dot2c_f32_bf16_dpp v242, v114, v8 row_newbcast:6 row_mask:0xf bank_mask:0xf
	v_dot2c_f32_bf16_dpp v242, v115, v9 row_newbcast:6 row_mask:0xf bank_mask:0xf
	v_dot2c_f32_bf16_dpp v242, v116, v10 row_newbcast:6 row_mask:0xf bank_mask:0xf
	v_dot2c_f32_bf16_dpp v242, v117, v11 row_newbcast:6 row_mask:0xf bank_mask:0xf
	v_dot2c_f32_bf16_dpp v242, v118, v12 row_newbcast:6 row_mask:0xf bank_mask:0xf
	v_dot2c_f32_bf16_dpp v242, v119, v13 row_newbcast:6 row_mask:0xf bank_mask:0xf
	v_dot2c_f32_bf16_dpp v242, v120, v14 row_newbcast:6 row_mask:0xf bank_mask:0xf
	v_dot2c_f32_bf16_dpp v242, v121, v15 row_newbcast:6 row_mask:0xf bank_mask:0xf
	v_mov_b32_e32 v243, v16
	v_dot2c_f32_bf16_dpp v243, v114, v8 row_newbcast:7 row_mask:0xf bank_mask:0xf
	v_dot2c_f32_bf16_dpp v243, v115, v9 row_newbcast:7 row_mask:0xf bank_mask:0xf
	v_dot2c_f32_bf16_dpp v243, v116, v10 row_newbcast:7 row_mask:0xf bank_mask:0xf
	v_dot2c_f32_bf16_dpp v243, v117, v11 row_newbcast:7 row_mask:0xf bank_mask:0xf
	v_dot2c_f32_bf16_dpp v243, v118, v12 row_newbcast:7 row_mask:0xf bank_mask:0xf
	v_dot2c_f32_bf16_dpp v243, v119, v13 row_newbcast:7 row_mask:0xf bank_mask:0xf
	v_dot2c_f32_bf16_dpp v243, v120, v14 row_newbcast:7 row_mask:0xf bank_mask:0xf
	v_dot2c_f32_bf16_dpp v243, v121, v15 row_newbcast:7 row_mask:0xf bank_mask:0xf
	v_mov_b32_e32 v244, v16
	v_dot2c_f32_bf16_dpp v244, v114, v8 row_newbcast:8 row_mask:0xf bank_mask:0xf
	v_dot2c_f32_bf16_dpp v244, v115, v9 row_newbcast:8 row_mask:0xf bank_mask:0xf
	v_dot2c_f32_bf16_dpp v244, v116, v10 row_newbcast:8 row_mask:0xf bank_mask:0xf
	v_dot2c_f32_bf16_dpp v244, v117, v11 row_newbcast:8 row_mask:0xf bank_mask:0xf
	v_dot2c_f32_bf16_dpp v244, v118, v12 row_newbcast:8 row_mask:0xf bank_mask:0xf
	v_dot2c_f32_bf16_dpp v244, v119, v13 row_newbcast:8 row_mask:0xf bank_mask:0xf
	v_dot2c_f32_bf16_dpp v244, v120, v14 row_newbcast:8 row_mask:0xf bank_mask:0xf
	v_dot2c_f32_bf16_dpp v244, v121, v15 row_newbcast:8 row_mask:0xf bank_mask:0xf
	v_mov_b32_e32 v245, v16
	v_dot2c_f32_bf16_dpp v245, v114, v8 row_newbcast:9 row_mask:0xf bank_mask:0xf
	v_dot2c_f32_bf16_dpp v245, v115, v9 row_newbcast:9 row_mask:0xf bank_mask:0xf
	v_dot2c_f32_bf16_dpp v245, v116, v10 row_newbcast:9 row_mask:0xf bank_mask:0xf
	v_dot2c_f32_bf16_dpp v245, v117, v11 row_newbcast:9 row_mask:0xf bank_mask:0xf
	v_dot2c_f32_bf16_dpp v245, v118, v12 row_newbcast:9 row_mask:0xf bank_mask:0xf
	v_dot2c_f32_bf16_dpp v245, v119, v13 row_newbcast:9 row_mask:0xf bank_mask:0xf
	v_dot2c_f32_bf16_dpp v245, v120, v14 row_newbcast:9 row_mask:0xf bank_mask:0xf
	v_dot2c_f32_bf16_dpp v245, v121, v15 row_newbcast:9 row_mask:0xf bank_mask:0xf
	v_mov_b32_e32 v246, v16
	v_dot2c_f32_bf16_dpp v246, v114, v8 row_newbcast:10 row_mask:0xf bank_mask:0xf
	v_dot2c_f32_bf16_dpp v246, v115, v9 row_newbcast:10 row_mask:0xf bank_mask:0xf
	v_dot2c_f32_bf16_dpp v246, v116, v10 row_newbcast:10 row_mask:0xf bank_mask:0xf
	v_dot2c_f32_bf16_dpp v246, v117, v11 row_newbcast:10 row_mask:0xf bank_mask:0xf
	v_dot2c_f32_bf16_dpp v246, v118, v12 row_newbcast:10 row_mask:0xf bank_mask:0xf
	v_dot2c_f32_bf16_dpp v246, v119, v13 row_newbcast:10 row_mask:0xf bank_mask:0xf
	v_dot2c_f32_bf16_dpp v246, v120, v14 row_newbcast:10 row_mask:0xf bank_mask:0xf
	v_dot2c_f32_bf16_dpp v246, v121, v15 row_newbcast:10 row_mask:0xf bank_mask:0xf
	v_mov_b32_e32 v247, v16
	v_dot2c_f32_bf16_dpp v247, v114, v8 row_newbcast:11 row_mask:0xf bank_mask:0xf
	v_dot2c_f32_bf16_dpp v247, v115, v9 row_newbcast:11 row_mask:0xf bank_mask:0xf
	v_dot2c_f32_bf16_dpp v247, v116, v10 row_newbcast:11 row_mask:0xf bank_mask:0xf
	v_dot2c_f32_bf16_dpp v247, v117, v11 row_newbcast:11 row_mask:0xf bank_mask:0xf
	v_dot2c_f32_bf16_dpp v247, v118, v12 row_newbcast:11 row_mask:0xf bank_mask:0xf
	v_dot2c_f32_bf16_dpp v247, v119, v13 row_newbcast:11 row_mask:0xf bank_mask:0xf
	v_dot2c_f32_bf16_dpp v247, v120, v14 row_newbcast:11 row_mask:0xf bank_mask:0xf
	v_dot2c_f32_bf16_dpp v247, v121, v15 row_newbcast:11 row_mask:0xf bank_mask:0xf
	v_mov_b32_e32 v248, v16
	v_dot2c_f32_bf16_dpp v248, v114, v8 row_newbcast:12 row_mask:0xf bank_mask:0xf
	v_dot2c_f32_bf16_dpp v248, v115, v9 row_newbcast:12 row_mask:0xf bank_mask:0xf
	v_dot2c_f32_bf16_dpp v248, v116, v10 row_newbcast:12 row_mask:0xf bank_mask:0xf
	v_dot2c_f32_bf16_dpp v248, v117, v11 row_newbcast:12 row_mask:0xf bank_mask:0xf
	v_dot2c_f32_bf16_dpp v248, v118, v12 row_newbcast:12 row_mask:0xf bank_mask:0xf
	v_dot2c_f32_bf16_dpp v248, v119, v13 row_newbcast:12 row_mask:0xf bank_mask:0xf
	v_dot2c_f32_bf16_dpp v248, v120, v14 row_newbcast:12 row_mask:0xf bank_mask:0xf
	v_dot2c_f32_bf16_dpp v248, v121, v15 row_newbcast:12 row_mask:0xf bank_mask:0xf
	v_mov_b32_e32 v249, v16
	v_dot2c_f32_bf16_dpp v249, v114, v8 row_newbcast:13 row_mask:0xf bank_mask:0xf
	v_dot2c_f32_bf16_dpp v249, v115, v9 row_newbcast:13 row_mask:0xf bank_mask:0xf
	v_dot2c_f32_bf16_dpp v249, v116, v10 row_newbcast:13 row_mask:0xf bank_mask:0xf
	v_dot2c_f32_bf16_dpp v249, v117, v11 row_newbcast:13 row_mask:0xf bank_mask:0xf
	v_dot2c_f32_bf16_dpp v249, v118, v12 row_newbcast:13 row_mask:0xf bank_mask:0xf
	v_dot2c_f32_bf16_dpp v249, v119, v13 row_newbcast:13 row_mask:0xf bank_mask:0xf
; __device__ __forceinline__ void gl1_item(PREF p, int l, int item, bool valid, LAS unsigned char* pl, int sw, int lane) {
;     ...
;             for (int ss = 0; ss < 16; ++ss) { const int s = g4 * 16 + ss; const int i = d ? 63 - s : s;
;                 float z = bup;
; #pragma unroll
;                 for (int r2 = 0; r2 < 8; ++r2) { const unsigned w = (unsigned)__builtin_amdgcn_readlane((int)lrp[r2], i);
;                     z = __builtin_amdgcn_fdot2_f32_bf16(__builtin_bit_cast(bf16x2_t, w), __builtin_bit_cast(bf16x2_t, wupp[r2]), z, false); }
;                 gv[ss] = -(fmaxf(-z, 0.f) + __logf(1.f + __expf(-fabsf(z)))) * (1.f / 16.f);
;                 __builtin_amdgcn_sched_barrier(0);
;             }
; #pragma unroll
;             for (int ss = 0; ss < 16; ++ss) { const int s = g4 * 16 + ss; const int i = d ? 63 - s : s; const size_t rowi = (size_t)(row0 + i * rstride);
;                 bc += gv[ss];
;                 const float en = __expf(-bc), ep = __expf(bc);
	v_dot2c_f32_bf16_dpp v249, v120, v14 row_newbcast:13 row_mask:0xf bank_mask:0xf
	v_dot2c_f32_bf16_dpp v249, v121, v15 row_newbcast:13 row_mask:0xf bank_mask:0xf
	v_mov_b32_e32 v250, v16
	v_dot2c_f32_bf16_dpp v250, v114, v8 row_newbcast:14 row_mask:0xf bank_mask:0xf
	v_dot2c_f32_bf16_dpp v250, v115, v9 row_newbcast:14 row_mask:0xf bank_mask:0xf
	v_dot2c_f32_bf16_dpp v250, v116, v10 row_newbcast:14 row_mask:0xf bank_mask:0xf
	v_dot2c_f32_bf16_dpp v250, v117, v11 row_newbcast:14 row_mask:0xf bank_mask:0xf
	v_dot2c_f32_bf16_dpp v250, v118, v12 row_newbcast:14 row_mask:0xf bank_mask:0xf
	v_dot2c_f32_bf16_dpp v250, v119, v13 row_newbcast:14 row_mask:0xf bank_mask:0xf
	v_dot2c_f32_bf16_dpp v250, v120, v14 row_newbcast:14 row_mask:0xf bank_mask:0xf
	v_dot2c_f32_bf16_dpp v250, v121, v15 row_newbcast:14 row_mask:0xf bank_mask:0xf
	v_mov_b32_e32 v251, v16
	v_dot2c_f32_bf16_dpp v251, v114, v8 row_newbcast:15 row_mask:0xf bank_mask:0xf
	v_dot2c_f32_bf16_dpp v251, v115, v9 row_newbcast:15 row_mask:0xf bank_mask:0xf
	v_dot2c_f32_bf16_dpp v251, v116, v10 row_newbcast:15 row_mask:0xf bank_mask:0xf
	v_dot2c_f32_bf16_dpp v251, v117, v11 row_newbcast:15 row_mask:0xf bank_mask:0xf
	v_dot2c_f32_bf16_dpp v251, v118, v12 row_newbcast:15 row_mask:0xf bank_mask:0xf
	v_dot2c_f32_bf16_dpp v251, v119, v13 row_newbcast:15 row_mask:0xf bank_mask:0xf
	v_dot2c_f32_bf16_dpp v251, v120, v14 row_newbcast:15 row_mask:0xf bank_mask:0xf
	v_dot2c_f32_bf16_dpp v251, v121, v15 row_newbcast:15 row_mask:0xf bank_mask:0xf
	s_nop 2
	v_mul_f32_e64 v18, |v236|, s1
	v_mul_f32_e64 v19, |v237|, s1
	v_mul_f32_e64 v20, |v238|, s1
	v_mul_f32_e64 v21, |v239|, s1
	v_mul_f32_e64 v22, |v240|, s1
	v_mul_f32_e64 v23, |v241|, s1
	v_mul_f32_e64 v24, |v242|, s1
	v_mul_f32_e64 v25, |v243|, s1
	v_mul_f32_e64 v26, |v244|, s1
	v_mul_f32_e64 v27, |v245|, s1
	v_mul_f32_e64 v28, |v246|, s1
	v_mul_f32_e64 v29, |v247|, s1
	v_mul_f32_e64 v30, |v248|, s1
	v_mul_f32_e64 v31, |v249|, s1
	v_mul_f32_e64 v32, |v250|, s1
	v_mul_f32_e64 v33, |v251|, s1
	v_exp_f32_e32 v18, v18
	v_exp_f32_e32 v19, v19
	v_exp_f32_e32 v20, v20
	v_exp_f32_e32 v21, v21
	v_exp_f32_e32 v22, v22
	v_exp_f32_e32 v23, v23
	v_exp_f32_e32 v24, v24
	v_exp_f32_e32 v25, v25
	v_exp_f32_e32 v26, v26
	v_exp_f32_e32 v27, v27
	v_exp_f32_e32 v28, v28
	v_exp_f32_e32 v29, v29
	v_exp_f32_e32 v30, v30
	v_exp_f32_e32 v31, v31
	v_exp_f32_e32 v32, v32
	v_exp_f32_e32 v33, v33
	v_max_f32_e64 v236, -v236, 0
	v_max_f32_e64 v237, -v237, 0
	v_max_f32_e64 v238, -v238, 0
	v_max_f32_e64 v239, -v239, 0
	v_max_f32_e64 v240, -v240, 0
	v_max_f32_e64 v241, -v241, 0
	v_max_f32_e64 v242, -v242, 0
	v_max_f32_e64 v243, -v243, 0
	v_max_f32_e64 v244, -v244, 0
	v_max_f32_e64 v245, -v245, 0
	v_max_f32_e64 v246, -v246, 0
	v_max_f32_e64 v247, -v247, 0
	v_max_f32_e64 v248, -v248, 0
	v_max_f32_e64 v249, -v249, 0
	v_max_f32_e64 v250, -v250, 0
	v_max_f32_e64 v251, -v251, 0
	v_add_f32_e32 v18, 1.0, v18
	v_add_f32_e32 v19, 1.0, v19
	v_add_f32_e32 v20, 1.0, v20
	v_add_f32_e32 v21, 1.0, v21
	v_add_f32_e32 v22, 1.0, v22
	v_add_f32_e32 v23, 1.0, v23
	v_add_f32_e32 v24, 1.0, v24
	v_add_f32_e32 v25, 1.0, v25
	v_add_f32_e32 v26, 1.0, v26
	v_add_f32_e32 v27, 1.0, v27
	v_add_f32_e32 v28, 1.0, v28
	v_add_f32_e32 v29, 1.0, v29
	v_add_f32_e32 v30, 1.0, v30
	v_add_f32_e32 v31, 1.0, v31
	v_add_f32_e32 v32, 1.0, v32
	v_add_f32_e32 v33, 1.0, v33
	v_log_f32_e32 v18, v18
	v_log_f32_e32 v19, v19
	v_log_f32_e32 v20, v20
	v_log_f32_e32 v21, v21
	v_log_f32_e32 v22, v22
	v_log_f32_e32 v23, v23
	v_log_f32_e32 v24, v24
	v_log_f32_e32 v25, v25
	v_log_f32_e32 v26, v26
	v_log_f32_e32 v27, v27
	v_log_f32_e32 v28, v28
	v_log_f32_e32 v29, v29
	v_log_f32_e32 v30, v30
	v_log_f32_e32 v31, v31
	v_log_f32_e32 v32, v32
	v_log_f32_e32 v33, v33
	v_fmac_f32_e32 v236, 0x3f317218, v18
	v_fmac_f32_e32 v237, 0x3f317218, v19
	v_fmac_f32_e32 v238, 0x3f317218, v20
	v_fmac_f32_e32 v239, 0x3f317218, v21
	v_fmac_f32_e32 v240, 0x3f317218, v22
	v_fmac_f32_e32 v241, 0x3f317218, v23
	v_fmac_f32_e32 v242, 0x3f317218, v24
	v_fmac_f32_e32 v243, 0x3f317218, v25
	v_fmac_f32_e32 v244, 0x3f317218, v26
	v_fmac_f32_e32 v245, 0x3f317218, v27
	v_fmac_f32_e32 v246, 0x3f317218, v28
	v_fmac_f32_e32 v247, 0x3f317218, v29
	v_fmac_f32_e32 v248, 0x3f317218, v30
	v_fmac_f32_e32 v249, 0x3f317218, v31
	v_fmac_f32_e32 v250, 0x3f317218, v32
	v_fmac_f32_e32 v251, 0x3f317218, v33
	v_fma_f32 v70, v236, s49, v17
	v_fma_f32 v71, v237, s49, v70
	v_fma_f32 v72, v238, s49, v71
	v_fma_f32 v73, v239, s49, v72
	v_fma_f32 v74, v240, s49, v73
	v_fma_f32 v75, v241, s49, v74
	v_fma_f32 v76, v242, s49, v75
	v_fma_f32 v77, v243, s49, v76
	v_fma_f32 v78, v244, s49, v77
	v_fma_f32 v79, v245, s49, v78
	v_fma_f32 v80, v246, s49, v79
	v_fma_f32 v81, v247, s49, v80
	v_fma_f32 v82, v248, s49, v81
	v_fma_f32 v83, v249, s49, v82
	v_fma_f32 v84, v250, s49, v83
	v_fma_f32 v85, v251, s49, v84
	v_mov_b32_e32 v17, v85
	s_waitcnt vmcnt(32)
; __device__ __forceinline__ unsigned f2bf(float f) { unsigned r; asm("v_cvt_pk_bf16_f32 %0, %1, %1" : "=v"(r) : "v"(f)); return r & 0xffffu; }
; __device__ __forceinline__ void gl1_item(PREF p, int l, int item, bool valid, LAS unsigned char* pl, int sw, int lane) {
;     ...
;             if (g4 < 3) {
; #pragma unroll
;                 for (int ss = 0; ss < 16; ++ss) { const int s = (g4 + 1) * 16 + ss; const int i = d ? 63 - s : s; const bf16_t* pr = P + (size_t)(row0 + i * rstride) * PW + h * 64 + lane;
;                     qn[ss] = __builtin_bit_cast(float, (unsigned)pr[1024]); kn[ss] = __builtin_bit_cast(float, (unsigned)pr[1280]); }
;                 __builtin_amdgcn_sched_barrier(0);
;             }
;     ...
;             for (int ss = 0; ss < 16; ++ss) { const int s = g4 * 16 + ss; const int i = d ? 63 - s : s; const size_t rowi = (size_t)(row0 + i * rstride);
;                 bc += gv[ss];
;                 const float en = __expf(-bc), ep = __expf(bc);
;                 const float kt = kc[ss] * en, qt = qc[ss] * 0.125f * ep;
;                 const unsigned ktb = f2bf(kt);
;                 sKt[lane * 72 + i] = (bf16_t)ktb;
;                 QK[rowi * 1024 + d * 512 + h * 64 + lane] = (bf16_t)f2bf(qt);
;                 QK[rowi * 1024 + d * 512 + 256 + h * 64 + lane] = (bf16_t)ktb;
	global_load_short_d16_hi v180, v134, s[6:7]
	global_load_short_d16_hi v196, v134, s[6:7] offset:512
	s_add_u32 s6, s6, s54
	s_addc_u32 s7, s7, s55
	global_load_short_d16_hi v181, v134, s[6:7]
	global_load_short_d16_hi v197, v134, s[6:7] offset:512
	s_add_u32 s6, s6, s54
	s_addc_u32 s7, s7, s55
	global_load_short_d16_hi v182, v134, s[6:7]
	global_load_short_d16_hi v198, v134, s[6:7] offset:512
	s_add_u32 s6, s6, s54
	s_addc_u32 s7, s7, s55
	global_load_short_d16_hi v183, v134, s[6:7]
	global_load_short_d16_hi v199, v134, s[6:7] offset:512
	s_add_u32 s6, s6, s54
	s_addc_u32 s7, s7, s55
	global_load_short_d16_hi v184, v134, s[6:7]
	global_load_short_d16_hi v200, v134, s[6:7] offset:512
	s_add_u32 s6, s6, s54
	s_addc_u32 s7, s7, s55
	global_load_short_d16_hi v185, v134, s[6:7]
	global_load_short_d16_hi v201, v134, s[6:7] offset:512
	s_add_u32 s6, s6, s54
	s_addc_u32 s7, s7, s55
	global_load_short_d16_hi v186, v134, s[6:7]
	global_load_short_d16_hi v202, v134, s[6:7] offset:512
	s_add_u32 s6, s6, s54
	s_addc_u32 s7, s7, s55
	global_load_short_d16_hi v187, v134, s[6:7]
	global_load_short_d16_hi v203, v134, s[6:7] offset:512
	s_add_u32 s6, s6, s54
	s_addc_u32 s7, s7, s55
	global_load_short_d16_hi v188, v134, s[6:7]
	global_load_short_d16_hi v204, v134, s[6:7] offset:512
	s_add_u32 s6, s6, s54
	s_addc_u32 s7, s7, s55
	global_load_short_d16_hi v189, v134, s[6:7]
	global_load_short_d16_hi v205, v134, s[6:7] offset:512
	s_add_u32 s6, s6, s54
	s_addc_u32 s7, s7, s55
	global_load_short_d16_hi v190, v134, s[6:7]
	global_load_short_d16_hi v206, v134, s[6:7] offset:512
	s_add_u32 s6, s6, s54
	s_addc_u32 s7, s7, s55
	global_load_short_d16_hi v191, v134, s[6:7]
	global_load_short_d16_hi v207, v134, s[6:7] offset:512
	s_add_u32 s6, s6, s54
	s_addc_u32 s7, s7, s55
	global_load_short_d16_hi v192, v134, s[6:7]
	global_load_short_d16_hi v208, v134, s[6:7] offset:512
	s_add_u32 s6, s6, s54
	s_addc_u32 s7, s7, s55
	global_load_short_d16_hi v193, v134, s[6:7]
	global_load_short_d16_hi v209, v134, s[6:7] offset:512
	s_add_u32 s6, s6, s54
	s_addc_u32 s7, s7, s55
	global_load_short_d16_hi v194, v134, s[6:7]
	global_load_short_d16_hi v210, v134, s[6:7] offset:512
	s_add_u32 s6, s6, s54
	s_addc_u32 s7, s7, s55
	global_load_short_d16_hi v195, v134, s[6:7]
	global_load_short_d16_hi v211, v134, s[6:7] offset:512
	s_add_u32 s6, s6, s54
	s_addc_u32 s7, s7, s55
	v_mul_f32_e32 v18, 0xbfb8aa3b, v70
	v_mul_f32_e32 v19, 0xbfb8aa3b, v71
	v_mul_f32_e32 v20, 0xbfb8aa3b, v72
	v_mul_f32_e32 v21, 0xbfb8aa3b, v73
	v_mul_f32_e32 v22, 0xbfb8aa3b, v74
	v_mul_f32_e32 v23, 0xbfb8aa3b, v75
	v_mul_f32_e32 v24, 0xbfb8aa3b, v76
	v_mul_f32_e32 v25, 0xbfb8aa3b, v77
	v_mul_f32_e32 v26, 0xbfb8aa3b, v78
	v_mul_f32_e32 v27, 0xbfb8aa3b, v79
	v_mul_f32_e32 v28, 0xbfb8aa3b, v80
	v_mul_f32_e32 v29, 0xbfb8aa3b, v81
	v_mul_f32_e32 v30, 0xbfb8aa3b, v82
	v_mul_f32_e32 v31, 0xbfb8aa3b, v83
	v_mul_f32_e32 v32, 0xbfb8aa3b, v84
	v_mul_f32_e32 v33, 0xbfb8aa3b, v85
	v_exp_f32_e64 v236, -v18
	v_exp_f32_e64 v237, -v19
	v_exp_f32_e64 v238, -v20
	v_exp_f32_e64 v239, -v21
	v_exp_f32_e64 v240, -v22
	v_exp_f32_e64 v241, -v23
	v_exp_f32_e64 v242, -v24
	v_exp_f32_e64 v243, -v25
	v_exp_f32_e64 v244, -v26
	v_exp_f32_e64 v245, -v27
	v_exp_f32_e64 v246, -v28
	v_exp_f32_e64 v247, -v29
	v_exp_f32_e64 v248, -v30
	v_exp_f32_e64 v249, -v31
	v_exp_f32_e64 v250, -v32
	v_exp_f32_e64 v251, -v33
	v_exp_f32_e32 v18, v18
	v_exp_f32_e32 v19, v19
	v_exp_f32_e32 v20, v20
	v_exp_f32_e32 v21, v21
	v_exp_f32_e32 v22, v22
	v_exp_f32_e32 v23, v23
	v_exp_f32_e32 v24, v24
	v_exp_f32_e32 v25, v25
	v_exp_f32_e32 v26, v26
	v_exp_f32_e32 v27, v27
	v_exp_f32_e32 v28, v28
	v_exp_f32_e32 v29, v29
	v_exp_f32_e32 v30, v30
	v_exp_f32_e32 v31, v31
	v_exp_f32_e32 v32, v32
	v_exp_f32_e32 v33, v33
	v_mul_f32_e32 v18, v18, v164
	v_mul_f32_e32 v19, v19, v165
	v_mul_f32_e32 v20, v20, v166
	v_mul_f32_e32 v21, v21, v167
	v_mul_f32_e32 v22, v22, v168
	v_mul_f32_e32 v23, v23, v169
	v_mul_f32_e32 v24, v24, v170
	v_mul_f32_e32 v25, v25, v171
	v_mul_f32_e32 v26, v26, v172
	v_mul_f32_e32 v27, v27, v173
	v_mul_f32_e32 v28, v28, v174
	v_mul_f32_e32 v29, v29, v175
	v_mul_f32_e32 v30, v30, v176
	v_mul_f32_e32 v31, v31, v177
	v_mul_f32_e32 v32, v32, v178
	v_mul_f32_e32 v33, v33, v179
	v_mul_f32_e32 v70, 0x3e000000, v148
	v_mul_f32_e32 v71, 0x3e000000, v149
	v_mul_f32_e32 v72, 0x3e000000, v150
	v_mul_f32_e32 v73, 0x3e000000, v151
	v_mul_f32_e32 v74, 0x3e000000, v152
	v_mul_f32_e32 v75, 0x3e000000, v153
	v_mul_f32_e32 v76, 0x3e000000, v154
	v_mul_f32_e32 v77, 0x3e000000, v155
	v_mul_f32_e32 v78, 0x3e000000, v156
	v_mul_f32_e32 v79, 0x3e000000, v157
	v_mul_f32_e32 v80, 0x3e000000, v158
	v_mul_f32_e32 v81, 0x3e000000, v159
	v_mul_f32_e32 v82, 0x3e000000, v160
	v_mul_f32_e32 v83, 0x3e000000, v161
	v_mul_f32_e32 v84, 0x3e000000, v162
	v_mul_f32_e32 v85, 0x3e000000, v163
	v_mul_f32_e32 v236, v70, v236
	v_mul_f32_e32 v237, v71, v237
	v_mul_f32_e32 v238, v72, v238
	v_mul_f32_e32 v239, v73, v239
	v_mul_f32_e32 v240, v74, v240
	v_mul_f32_e32 v241, v75, v241
	v_mul_f32_e32 v242, v76, v242
	v_mul_f32_e32 v243, v77, v243
	v_mul_f32_e32 v244, v78, v244
	v_mul_f32_e32 v245, v79, v245
	v_mul_f32_e32 v246, v80, v246
	v_mul_f32_e32 v247, v81, v247
	v_mul_f32_e32 v248, v82, v248
	v_mul_f32_e32 v249, v83, v249
	v_mul_f32_e32 v250, v84, v250
	v_mul_f32_e32 v251, v85, v251
	v_cvt_pk_bf16_f32 v18, v18, v236
	v_cvt_pk_bf16_f32 v19, v19, v237
	v_cvt_pk_bf16_f32 v20, v20, v238
	v_cvt_pk_bf16_f32 v21, v21, v239
	v_cvt_pk_bf16_f32 v22, v22, v240
	v_cvt_pk_bf16_f32 v23, v23, v241
	v_cvt_pk_bf16_f32 v24, v24, v242
	v_cvt_pk_bf16_f32 v25, v25, v243
	v_cvt_pk_bf16_f32 v26, v26, v244
	v_cvt_pk_bf16_f32 v27, v27, v245
; __device__ __forceinline__ unsigned f2bf(float f) { unsigned r; asm("v_cvt_pk_bf16_f32 %0, %1, %1" : "=v"(r) : "v"(f)); return r & 0xffffu; }
; __device__ __forceinline__ void gl1_item(PREF p, int l, int item, bool valid, LAS unsigned char* pl, int sw, int lane) {
;     ...
;             for (int ss = 0; ss < 16; ++ss) { const int s = g4 * 16 + ss; const int i = d ? 63 - s : s;
;                 float z = bup;
; #pragma unroll
;                 for (int r2 = 0; r2 < 8; ++r2) { const unsigned w = (unsigned)__builtin_amdgcn_readlane((int)lrp[r2], i);
;                     z = __builtin_amdgcn_fdot2_f32_bf16(__builtin_bit_cast(bf16x2_t, w), __builtin_bit_cast(bf16x2_t, wupp[r2]), z, false); }
;     ...
;             for (int ss = 0; ss < 16; ++ss) { const int s = g4 * 16 + ss; const int i = d ? 63 - s : s; const size_t rowi = (size_t)(row0 + i * rstride);
;                 bc += gv[ss];
;                 const float en = __expf(-bc), ep = __expf(bc);
;                 const float kt = kc[ss] * en, qt = qc[ss] * 0.125f * ep;
;                 const unsigned ktb = f2bf(kt);
;                 sKt[lane * 72 + i] = (bf16_t)ktb;
;                 QK[rowi * 1024 + d * 512 + h * 64 + lane] = (bf16_t)f2bf(qt);
;                 QK[rowi * 1024 + d * 512 + 256 + h * 64 + lane] = (bf16_t)ktb;
;             }
	v_cvt_pk_bf16_f32 v28, v28, v246
	v_cvt_pk_bf16_f32 v29, v29, v247
	v_cvt_pk_bf16_f32 v30, v30, v248
	v_cvt_pk_bf16_f32 v31, v31, v249
	v_cvt_pk_bf16_f32 v32, v32, v250
	v_cvt_pk_bf16_f32 v33, v33, v251
	ds_write_b16 v60, v18
	v_add_u32_e32 v60, v61, v60
	global_store_short_d16_hi v134, v18, s[4:5]
	global_store_short v134, v18, s[4:5] offset:512
	s_add_u32 s4, s4, s56
	s_addc_u32 s5, s5, s3
	ds_write_b16 v60, v19
	v_add_u32_e32 v60, v61, v60
	global_store_short_d16_hi v134, v19, s[4:5]
	global_store_short v134, v19, s[4:5] offset:512
	s_add_u32 s4, s4, s56
	s_addc_u32 s5, s5, s3
	ds_write_b16 v60, v20
	v_add_u32_e32 v60, v61, v60
	global_store_short_d16_hi v134, v20, s[4:5]
	global_store_short v134, v20, s[4:5] offset:512
	s_add_u32 s4, s4, s56
	s_addc_u32 s5, s5, s3
	ds_write_b16 v60, v21
	v_add_u32_e32 v60, v61, v60
	global_store_short_d16_hi v134, v21, s[4:5]
	global_store_short v134, v21, s[4:5] offset:512
	s_add_u32 s4, s4, s56
	s_addc_u32 s5, s5, s3
	ds_write_b16 v60, v22
	v_add_u32_e32 v60, v61, v60
	global_store_short_d16_hi v134, v22, s[4:5]
	global_store_short v134, v22, s[4:5] offset:512
	s_add_u32 s4, s4, s56
	s_addc_u32 s5, s5, s3
	ds_write_b16 v60, v23
	v_add_u32_e32 v60, v61, v60
	global_store_short_d16_hi v134, v23, s[4:5]
	global_store_short v134, v23, s[4:5] offset:512
	s_add_u32 s4, s4, s56
	s_addc_u32 s5, s5, s3
	ds_write_b16 v60, v24
	v_add_u32_e32 v60, v61, v60
	global_store_short_d16_hi v134, v24, s[4:5]
	global_store_short v134, v24, s[4:5] offset:512
	s_add_u32 s4, s4, s56
	s_addc_u32 s5, s5, s3
	ds_write_b16 v60, v25
	v_add_u32_e32 v60, v61, v60
	global_store_short_d16_hi v134, v25, s[4:5]
	global_store_short v134, v25, s[4:5] offset:512
	s_add_u32 s4, s4, s56
	s_addc_u32 s5, s5, s3
	ds_write_b16 v60, v26
	v_add_u32_e32 v60, v61, v60
	global_store_short_d16_hi v134, v26, s[4:5]
	global_store_short v134, v26, s[4:5] offset:512
	s_add_u32 s4, s4, s56
	s_addc_u32 s5, s5, s3
	ds_write_b16 v60, v27
	v_add_u32_e32 v60, v61, v60
	global_store_short_d16_hi v134, v27, s[4:5]
	global_store_short v134, v27, s[4:5] offset:512
	s_add_u32 s4, s4, s56
	s_addc_u32 s5, s5, s3
	ds_write_b16 v60, v28
	v_add_u32_e32 v60, v61, v60
	global_store_short_d16_hi v134, v28, s[4:5]
	global_store_short v134, v28, s[4:5] offset:512
	s_add_u32 s4, s4, s56
	s_addc_u32 s5, s5, s3
	ds_write_b16 v60, v29
	v_add_u32_e32 v60, v61, v60
	global_store_short_d16_hi v134, v29, s[4:5]
	global_store_short v134, v29, s[4:5] offset:512
	s_add_u32 s4, s4, s56
	s_addc_u32 s5, s5, s3
	ds_write_b16 v60, v30
	v_add_u32_e32 v60, v61, v60
	global_store_short_d16_hi v134, v30, s[4:5]
	global_store_short v134, v30, s[4:5] offset:512
	s_add_u32 s4, s4, s56
	s_addc_u32 s5, s5, s3
	ds_write_b16 v60, v31
	v_add_u32_e32 v60, v61, v60
	global_store_short_d16_hi v134, v31, s[4:5]
	global_store_short v134, v31, s[4:5] offset:512
	s_add_u32 s4, s4, s56
	s_addc_u32 s5, s5, s3
	ds_write_b16 v60, v32
	v_add_u32_e32 v60, v61, v60
	global_store_short_d16_hi v134, v32, s[4:5]
	global_store_short v134, v32, s[4:5] offset:512
	s_add_u32 s4, s4, s56
	s_addc_u32 s5, s5, s3
	ds_write_b16 v60, v33
	v_add_u32_e32 v60, v61, v60
	global_store_short_d16_hi v134, v33, s[4:5]
	global_store_short v134, v33, s[4:5] offset:512
	s_add_u32 s4, s4, s56
	s_addc_u32 s5, s5, s3
	v_mov_b32_e32 v236, v16
	v_dot2c_f32_bf16_dpp v236, v122, v8 row_newbcast:0 row_mask:0xf bank_mask:0xf
	v_dot2c_f32_bf16_dpp v236, v123, v9 row_newbcast:0 row_mask:0xf bank_mask:0xf
	v_dot2c_f32_bf16_dpp v236, v124, v10 row_newbcast:0 row_mask:0xf bank_mask:0xf
	v_dot2c_f32_bf16_dpp v236, v125, v11 row_newbcast:0 row_mask:0xf bank_mask:0xf
	v_dot2c_f32_bf16_dpp v236, v126, v12 row_newbcast:0 row_mask:0xf bank_mask:0xf
	v_dot2c_f32_bf16_dpp v236, v127, v13 row_newbcast:0 row_mask:0xf bank_mask:0xf
	v_dot2c_f32_bf16_dpp v236, v128, v14 row_newbcast:0 row_mask:0xf bank_mask:0xf
	v_dot2c_f32_bf16_dpp v236, v129, v15 row_newbcast:0 row_mask:0xf bank_mask:0xf
	v_mov_b32_e32 v237, v16
	v_dot2c_f32_bf16_dpp v237, v122, v8 row_newbcast:1 row_mask:0xf bank_mask:0xf
	v_dot2c_f32_bf16_dpp v237, v123, v9 row_newbcast:1 row_mask:0xf bank_mask:0xf
	v_dot2c_f32_bf16_dpp v237, v124, v10 row_newbcast:1 row_mask:0xf bank_mask:0xf
	v_dot2c_f32_bf16_dpp v237, v125, v11 row_newbcast:1 row_mask:0xf bank_mask:0xf
	v_dot2c_f32_bf16_dpp v237, v126, v12 row_newbcast:1 row_mask:0xf bank_mask:0xf
	v_dot2c_f32_bf16_dpp v237, v127, v13 row_newbcast:1 row_mask:0xf bank_mask:0xf
	v_dot2c_f32_bf16_dpp v237, v128, v14 row_newbcast:1 row_mask:0xf bank_mask:0xf
	v_dot2c_f32_bf16_dpp v237, v129, v15 row_newbcast:1 row_mask:0xf bank_mask:0xf
	v_mov_b32_e32 v238, v16
	v_dot2c_f32_bf16_dpp v238, v122, v8 row_newbcast:2 row_mask:0xf bank_mask:0xf
	v_dot2c_f32_bf16_dpp v238, v123, v9 row_newbcast:2 row_mask:0xf bank_mask:0xf
	v_dot2c_f32_bf16_dpp v238, v124, v10 row_newbcast:2 row_mask:0xf bank_mask:0xf
	v_dot2c_f32_bf16_dpp v238, v125, v11 row_newbcast:2 row_mask:0xf bank_mask:0xf
	v_dot2c_f32_bf16_dpp v238, v126, v12 row_newbcast:2 row_mask:0xf bank_mask:0xf
	v_dot2c_f32_bf16_dpp v238, v127, v13 row_newbcast:2 row_mask:0xf bank_mask:0xf
	v_dot2c_f32_bf16_dpp v238, v128, v14 row_newbcast:2 row_mask:0xf bank_mask:0xf
	v_dot2c_f32_bf16_dpp v238, v129, v15 row_newbcast:2 row_mask:0xf bank_mask:0xf
	v_mov_b32_e32 v239, v16
	v_dot2c_f32_bf16_dpp v239, v122, v8 row_newbcast:3 row_mask:0xf bank_mask:0xf
	v_dot2c_f32_bf16_dpp v239, v123, v9 row_newbcast:3 row_mask:0xf bank_mask:0xf
	v_dot2c_f32_bf16_dpp v239, v124, v10 row_newbcast:3 row_mask:0xf bank_mask:0xf
	v_dot2c_f32_bf16_dpp v239, v125, v11 row_newbcast:3 row_mask:0xf bank_mask:0xf
; __device__ __forceinline__ void gl1_item(PREF p, int l, int item, bool valid, LAS unsigned char* pl, int sw, int lane) {
;     ...
;             for (int ss = 0; ss < 16; ++ss) { const int s = g4 * 16 + ss; const int i = d ? 63 - s : s;
;                 float z = bup;
; #pragma unroll
;                 for (int r2 = 0; r2 < 8; ++r2) { const unsigned w = (unsigned)__builtin_amdgcn_readlane((int)lrp[r2], i);
;                     z = __builtin_amdgcn_fdot2_f32_bf16(__builtin_bit_cast(bf16x2_t, w), __builtin_bit_cast(bf16x2_t, wupp[r2]), z, false); }
	v_dot2c_f32_bf16_dpp v239, v126, v12 row_newbcast:3 row_mask:0xf bank_mask:0xf
	v_dot2c_f32_bf16_dpp v239, v127, v13 row_newbcast:3 row_mask:0xf bank_mask:0xf
	v_dot2c_f32_bf16_dpp v239, v128, v14 row_newbcast:3 row_mask:0xf bank_mask:0xf
	v_dot2c_f32_bf16_dpp v239, v129, v15 row_newbcast:3 row_mask:0xf bank_mask:0xf
	v_mov_b32_e32 v240, v16
	v_dot2c_f32_bf16_dpp v240, v122, v8 row_newbcast:4 row_mask:0xf bank_mask:0xf
	v_dot2c_f32_bf16_dpp v240, v123, v9 row_newbcast:4 row_mask:0xf bank_mask:0xf
	v_dot2c_f32_bf16_dpp v240, v124, v10 row_newbcast:4 row_mask:0xf bank_mask:0xf
	v_dot2c_f32_bf16_dpp v240, v125, v11 row_newbcast:4 row_mask:0xf bank_mask:0xf
	v_dot2c_f32_bf16_dpp v240, v126, v12 row_newbcast:4 row_mask:0xf bank_mask:0xf
	v_dot2c_f32_bf16_dpp v240, v127, v13 row_newbcast:4 row_mask:0xf bank_mask:0xf
	v_dot2c_f32_bf16_dpp v240, v128, v14 row_newbcast:4 row_mask:0xf bank_mask:0xf
	v_dot2c_f32_bf16_dpp v240, v129, v15 row_newbcast:4 row_mask:0xf bank_mask:0xf
	v_mov_b32_e32 v241, v16
	v_dot2c_f32_bf16_dpp v241, v122, v8 row_newbcast:5 row_mask:0xf bank_mask:0xf
	v_dot2c_f32_bf16_dpp v241, v123, v9 row_newbcast:5 row_mask:0xf bank_mask:0xf
	v_dot2c_f32_bf16_dpp v241, v124, v10 row_newbcast:5 row_mask:0xf bank_mask:0xf
	v_dot2c_f32_bf16_dpp v241, v125, v11 row_newbcast:5 row_mask:0xf bank_mask:0xf
	v_dot2c_f32_bf16_dpp v241, v126, v12 row_newbcast:5 row_mask:0xf bank_mask:0xf
	v_dot2c_f32_bf16_dpp v241, v127, v13 row_newbcast:5 row_mask:0xf bank_mask:0xf
	v_dot2c_f32_bf16_dpp v241, v128, v14 row_newbcast:5 row_mask:0xf bank_mask:0xf
	v_dot2c_f32_bf16_dpp v241, v129, v15 row_newbcast:5 row_mask:0xf bank_mask:0xf
	v_mov_b32_e32 v242, v16
	v_dot2c_f32_bf16_dpp v242, v122, v8 row_newbcast:6 row_mask:0xf bank_mask:0xf
	v_dot2c_f32_bf16_dpp v242, v123, v9 row_newbcast:6 row_mask:0xf bank_mask:0xf
	v_dot2c_f32_bf16_dpp v242, v124, v10 row_newbcast:6 row_mask:0xf bank_mask:0xf
	v_dot2c_f32_bf16_dpp v242, v125, v11 row_newbcast:6 row_mask:0xf bank_mask:0xf
	v_dot2c_f32_bf16_dpp v242, v126, v12 row_newbcast:6 row_mask:0xf bank_mask:0xf
	v_dot2c_f32_bf16_dpp v242, v127, v13 row_newbcast:6 row_mask:0xf bank_mask:0xf
	v_dot2c_f32_bf16_dpp v242, v128, v14 row_newbcast:6 row_mask:0xf bank_mask:0xf
	v_dot2c_f32_bf16_dpp v242, v129, v15 row_newbcast:6 row_mask:0xf bank_mask:0xf
	v_mov_b32_e32 v243, v16
	v_dot2c_f32_bf16_dpp v243, v122, v8 row_newbcast:7 row_mask:0xf bank_mask:0xf
	v_dot2c_f32_bf16_dpp v243, v123, v9 row_newbcast:7 row_mask:0xf bank_mask:0xf
	v_dot2c_f32_bf16_dpp v243, v124, v10 row_newbcast:7 row_mask:0xf bank_mask:0xf
	v_dot2c_f32_bf16_dpp v243, v125, v11 row_newbcast:7 row_mask:0xf bank_mask:0xf
	v_dot2c_f32_bf16_dpp v243, v126, v12 row_newbcast:7 row_mask:0xf bank_mask:0xf
	v_dot2c_f32_bf16_dpp v243, v127, v13 row_newbcast:7 row_mask:0xf bank_mask:0xf
	v_dot2c_f32_bf16_dpp v243, v128, v14 row_newbcast:7 row_mask:0xf bank_mask:0xf
	v_dot2c_f32_bf16_dpp v243, v129, v15 row_newbcast:7 row_mask:0xf bank_mask:0xf
	v_mov_b32_e32 v244, v16
	v_dot2c_f32_bf16_dpp v244, v122, v8 row_newbcast:8 row_mask:0xf bank_mask:0xf
	v_dot2c_f32_bf16_dpp v244, v123, v9 row_newbcast:8 row_mask:0xf bank_mask:0xf
	v_dot2c_f32_bf16_dpp v244, v124, v10 row_newbcast:8 row_mask:0xf bank_mask:0xf
	v_dot2c_f32_bf16_dpp v244, v125, v11 row_newbcast:8 row_mask:0xf bank_mask:0xf
	v_dot2c_f32_bf16_dpp v244, v126, v12 row_newbcast:8 row_mask:0xf bank_mask:0xf
	v_dot2c_f32_bf16_dpp v244, v127, v13 row_newbcast:8 row_mask:0xf bank_mask:0xf
	v_dot2c_f32_bf16_dpp v244, v128, v14 row_newbcast:8 row_mask:0xf bank_mask:0xf
	v_dot2c_f32_bf16_dpp v244, v129, v15 row_newbcast:8 row_mask:0xf bank_mask:0xf
	v_mov_b32_e32 v245, v16
	v_dot2c_f32_bf16_dpp v245, v122, v8 row_newbcast:9 row_mask:0xf bank_mask:0xf
	v_dot2c_f32_bf16_dpp v245, v123, v9 row_newbcast:9 row_mask:0xf bank_mask:0xf
	v_dot2c_f32_bf16_dpp v245, v124, v10 row_newbcast:9 row_mask:0xf bank_mask:0xf
	v_dot2c_f32_bf16_dpp v245, v125, v11 row_newbcast:9 row_mask:0xf bank_mask:0xf
	v_dot2c_f32_bf16_dpp v245, v126, v12 row_newbcast:9 row_mask:0xf bank_mask:0xf
	v_dot2c_f32_bf16_dpp v245, v127, v13 row_newbcast:9 row_mask:0xf bank_mask:0xf
	v_dot2c_f32_bf16_dpp v245, v128, v14 row_newbcast:9 row_mask:0xf bank_mask:0xf
	v_dot2c_f32_bf16_dpp v245, v129, v15 row_newbcast:9 row_mask:0xf bank_mask:0xf
	v_mov_b32_e32 v246, v16
	v_dot2c_f32_bf16_dpp v246, v122, v8 row_newbcast:10 row_mask:0xf bank_mask:0xf
	v_dot2c_f32_bf16_dpp v246, v123, v9 row_newbcast:10 row_mask:0xf bank_mask:0xf
	v_dot2c_f32_bf16_dpp v246, v124, v10 row_newbcast:10 row_mask:0xf bank_mask:0xf
	v_dot2c_f32_bf16_dpp v246, v125, v11 row_newbcast:10 row_mask:0xf bank_mask:0xf
	v_dot2c_f32_bf16_dpp v246, v126, v12 row_newbcast:10 row_mask:0xf bank_mask:0xf
	v_dot2c_f32_bf16_dpp v246, v127, v13 row_newbcast:10 row_mask:0xf bank_mask:0xf
	v_dot2c_f32_bf16_dpp v246, v128, v14 row_newbcast:10 row_mask:0xf bank_mask:0xf
	v_dot2c_f32_bf16_dpp v246, v129, v15 row_newbcast:10 row_mask:0xf bank_mask:0xf
	v_mov_b32_e32 v247, v16
	v_dot2c_f32_bf16_dpp v247, v122, v8 row_newbcast:11 row_mask:0xf bank_mask:0xf
	v_dot2c_f32_bf16_dpp v247, v123, v9 row_newbcast:11 row_mask:0xf bank_mask:0xf
	v_dot2c_f32_bf16_dpp v247, v124, v10 row_newbcast:11 row_mask:0xf bank_mask:0xf
	v_dot2c_f32_bf16_dpp v247, v125, v11 row_newbcast:11 row_mask:0xf bank_mask:0xf
	v_dot2c_f32_bf16_dpp v247, v126, v12 row_newbcast:11 row_mask:0xf bank_mask:0xf
	v_dot2c_f32_bf16_dpp v247, v127, v13 row_newbcast:11 row_mask:0xf bank_mask:0xf
	v_dot2c_f32_bf16_dpp v247, v128, v14 row_newbcast:11 row_mask:0xf bank_mask:0xf
	v_dot2c_f32_bf16_dpp v247, v129, v15 row_newbcast:11 row_mask:0xf bank_mask:0xf
; __device__ __forceinline__ void gl1_item(PREF p, int l, int item, bool valid, LAS unsigned char* pl, int sw, int lane) {
;     ...
;             for (int ss = 0; ss < 16; ++ss) { const int s = g4 * 16 + ss; const int i = d ? 63 - s : s;
;                 float z = bup;
; #pragma unroll
;                 for (int r2 = 0; r2 < 8; ++r2) { const unsigned w = (unsigned)__builtin_amdgcn_readlane((int)lrp[r2], i);
;                     z = __builtin_amdgcn_fdot2_f32_bf16(__builtin_bit_cast(bf16x2_t, w), __builtin_bit_cast(bf16x2_t, wupp[r2]), z, false); }
;                 gv[ss] = -(fmaxf(-z, 0.f) + __logf(1.f + __expf(-fabsf(z)))) * (1.f / 16.f);
;                 __builtin_amdgcn_sched_barrier(0);
;             }
; #pragma unroll
;             for (int ss = 0; ss < 16; ++ss) { const int s = g4 * 16 + ss; const int i = d ? 63 - s : s; const size_t rowi = (size_t)(row0 + i * rstride);
;                 bc += gv[ss];
;                 const float en = __expf(-bc), ep = __expf(bc);
	v_mov_b32_e32 v248, v16
	v_dot2c_f32_bf16_dpp v248, v122, v8 row_newbcast:12 row_mask:0xf bank_mask:0xf
	v_dot2c_f32_bf16_dpp v248, v123, v9 row_newbcast:12 row_mask:0xf bank_mask:0xf
	v_dot2c_f32_bf16_dpp v248, v124, v10 row_newbcast:12 row_mask:0xf bank_mask:0xf
	v_dot2c_f32_bf16_dpp v248, v125, v11 row_newbcast:12 row_mask:0xf bank_mask:0xf
	v_dot2c_f32_bf16_dpp v248, v126, v12 row_newbcast:12 row_mask:0xf bank_mask:0xf
	v_dot2c_f32_bf16_dpp v248, v127, v13 row_newbcast:12 row_mask:0xf bank_mask:0xf
	v_dot2c_f32_bf16_dpp v248, v128, v14 row_newbcast:12 row_mask:0xf bank_mask:0xf
	v_dot2c_f32_bf16_dpp v248, v129, v15 row_newbcast:12 row_mask:0xf bank_mask:0xf
	v_mov_b32_e32 v249, v16
	v_dot2c_f32_bf16_dpp v249, v122, v8 row_newbcast:13 row_mask:0xf bank_mask:0xf
	v_dot2c_f32_bf16_dpp v249, v123, v9 row_newbcast:13 row_mask:0xf bank_mask:0xf
	v_dot2c_f32_bf16_dpp v249, v124, v10 row_newbcast:13 row_mask:0xf bank_mask:0xf
	v_dot2c_f32_bf16_dpp v249, v125, v11 row_newbcast:13 row_mask:0xf bank_mask:0xf
	v_dot2c_f32_bf16_dpp v249, v126, v12 row_newbcast:13 row_mask:0xf bank_mask:0xf
	v_dot2c_f32_bf16_dpp v249, v127, v13 row_newbcast:13 row_mask:0xf bank_mask:0xf
	v_dot2c_f32_bf16_dpp v249, v128, v14 row_newbcast:13 row_mask:0xf bank_mask:0xf
	v_dot2c_f32_bf16_dpp v249, v129, v15 row_newbcast:13 row_mask:0xf bank_mask:0xf
	v_mov_b32_e32 v250, v16
	v_dot2c_f32_bf16_dpp v250, v122, v8 row_newbcast:14 row_mask:0xf bank_mask:0xf
	v_dot2c_f32_bf16_dpp v250, v123, v9 row_newbcast:14 row_mask:0xf bank_mask:0xf
	v_dot2c_f32_bf16_dpp v250, v124, v10 row_newbcast:14 row_mask:0xf bank_mask:0xf
	v_dot2c_f32_bf16_dpp v250, v125, v11 row_newbcast:14 row_mask:0xf bank_mask:0xf
	v_dot2c_f32_bf16_dpp v250, v126, v12 row_newbcast:14 row_mask:0xf bank_mask:0xf
	v_dot2c_f32_bf16_dpp v250, v127, v13 row_newbcast:14 row_mask:0xf bank_mask:0xf
	v_dot2c_f32_bf16_dpp v250, v128, v14 row_newbcast:14 row_mask:0xf bank_mask:0xf
	v_dot2c_f32_bf16_dpp v250, v129, v15 row_newbcast:14 row_mask:0xf bank_mask:0xf
	v_mov_b32_e32 v251, v16
	v_dot2c_f32_bf16_dpp v251, v122, v8 row_newbcast:15 row_mask:0xf bank_mask:0xf
	v_dot2c_f32_bf16_dpp v251, v123, v9 row_newbcast:15 row_mask:0xf bank_mask:0xf
	v_dot2c_f32_bf16_dpp v251, v124, v10 row_newbcast:15 row_mask:0xf bank_mask:0xf
	v_dot2c_f32_bf16_dpp v251, v125, v11 row_newbcast:15 row_mask:0xf bank_mask:0xf
	v_dot2c_f32_bf16_dpp v251, v126, v12 row_newbcast:15 row_mask:0xf bank_mask:0xf
	v_dot2c_f32_bf16_dpp v251, v127, v13 row_newbcast:15 row_mask:0xf bank_mask:0xf
	v_dot2c_f32_bf16_dpp v251, v128, v14 row_newbcast:15 row_mask:0xf bank_mask:0xf
	v_dot2c_f32_bf16_dpp v251, v129, v15 row_newbcast:15 row_mask:0xf bank_mask:0xf
	s_nop 2
	v_mul_f32_e64 v18, |v236|, s1
	v_mul_f32_e64 v19, |v237|, s1
	v_mul_f32_e64 v20, |v238|, s1
	v_mul_f32_e64 v21, |v239|, s1
	v_mul_f32_e64 v22, |v240|, s1
	v_mul_f32_e64 v23, |v241|, s1
	v_mul_f32_e64 v24, |v242|, s1
	v_mul_f32_e64 v25, |v243|, s1
	v_mul_f32_e64 v26, |v244|, s1
	v_mul_f32_e64 v27, |v245|, s1
	v_mul_f32_e64 v28, |v246|, s1
	v_mul_f32_e64 v29, |v247|, s1
	v_mul_f32_e64 v30, |v248|, s1
	v_mul_f32_e64 v31, |v249|, s1
	v_mul_f32_e64 v32, |v250|, s1
	v_mul_f32_e64 v33, |v251|, s1
	v_exp_f32_e32 v18, v18
	v_exp_f32_e32 v19, v19
	v_exp_f32_e32 v20, v20
	v_exp_f32_e32 v21, v21
	v_exp_f32_e32 v22, v22
	v_exp_f32_e32 v23, v23
	v_exp_f32_e32 v24, v24
	v_exp_f32_e32 v25, v25
	v_exp_f32_e32 v26, v26
	v_exp_f32_e32 v27, v27
	v_exp_f32_e32 v28, v28
	v_exp_f32_e32 v29, v29
	v_exp_f32_e32 v30, v30
	v_exp_f32_e32 v31, v31
	v_exp_f32_e32 v32, v32
	v_exp_f32_e32 v33, v33
	v_max_f32_e64 v236, -v236, 0
	v_max_f32_e64 v237, -v237, 0
	v_max_f32_e64 v238, -v238, 0
	v_max_f32_e64 v239, -v239, 0
	v_max_f32_e64 v240, -v240, 0
	v_max_f32_e64 v241, -v241, 0
	v_max_f32_e64 v242, -v242, 0
	v_max_f32_e64 v243, -v243, 0
	v_max_f32_e64 v244, -v244, 0
	v_max_f32_e64 v245, -v245, 0
	v_max_f32_e64 v246, -v246, 0
	v_max_f32_e64 v247, -v247, 0
	v_max_f32_e64 v248, -v248, 0
	v_max_f32_e64 v249, -v249, 0
	v_max_f32_e64 v250, -v250, 0
	v_max_f32_e64 v251, -v251, 0
	v_add_f32_e32 v18, 1.0, v18
	v_add_f32_e32 v19, 1.0, v19
	v_add_f32_e32 v20, 1.0, v20
	v_add_f32_e32 v21, 1.0, v21
	v_add_f32_e32 v22, 1.0, v22
	v_add_f32_e32 v23, 1.0, v23
	v_add_f32_e32 v24, 1.0, v24
	v_add_f32_e32 v25, 1.0, v25
	v_add_f32_e32 v26, 1.0, v26
	v_add_f32_e32 v27, 1.0, v27
	v_add_f32_e32 v28, 1.0, v28
	v_add_f32_e32 v29, 1.0, v29
	v_add_f32_e32 v30, 1.0, v30
	v_add_f32_e32 v31, 1.0, v31
	v_add_f32_e32 v32, 1.0, v32
	v_add_f32_e32 v33, 1.0, v33
	v_log_f32_e32 v18, v18
	v_log_f32_e32 v19, v19
	v_log_f32_e32 v20, v20
	v_log_f32_e32 v21, v21
	v_log_f32_e32 v22, v22
	v_log_f32_e32 v23, v23
	v_log_f32_e32 v24, v24
	v_log_f32_e32 v25, v25
	v_log_f32_e32 v26, v26
	v_log_f32_e32 v27, v27
	v_log_f32_e32 v28, v28
	v_log_f32_e32 v29, v29
	v_log_f32_e32 v30, v30
	v_log_f32_e32 v31, v31
	v_log_f32_e32 v32, v32
	v_log_f32_e32 v33, v33
	v_fmac_f32_e32 v236, 0x3f317218, v18
	v_fmac_f32_e32 v237, 0x3f317218, v19
	v_fmac_f32_e32 v238, 0x3f317218, v20
	v_fmac_f32_e32 v239, 0x3f317218, v21
	v_fmac_f32_e32 v240, 0x3f317218, v22
	v_fmac_f32_e32 v241, 0x3f317218, v23
	v_fmac_f32_e32 v242, 0x3f317218, v24
	v_fmac_f32_e32 v243, 0x3f317218, v25
	v_fmac_f32_e32 v244, 0x3f317218, v26
	v_fmac_f32_e32 v245, 0x3f317218, v27
	v_fmac_f32_e32 v246, 0x3f317218, v28
	v_fmac_f32_e32 v247, 0x3f317218, v29
	v_fmac_f32_e32 v248, 0x3f317218, v30
	v_fmac_f32_e32 v249, 0x3f317218, v31
	v_fmac_f32_e32 v250, 0x3f317218, v32
	v_fmac_f32_e32 v251, 0x3f317218, v33
	v_fma_f32 v70, v236, s49, v17
	v_fma_f32 v71, v237, s49, v70
	v_fma_f32 v72, v238, s49, v71
	v_fma_f32 v73, v239, s49, v72
	v_fma_f32 v74, v240, s49, v73
	v_fma_f32 v75, v241, s49, v74
	v_fma_f32 v76, v242, s49, v75
	v_fma_f32 v77, v243, s49, v76
	v_fma_f32 v78, v244, s49, v77
	v_fma_f32 v79, v245, s49, v78
	v_fma_f32 v80, v246, s49, v79
	v_fma_f32 v81, v247, s49, v80
	v_fma_f32 v82, v248, s49, v81
	v_fma_f32 v83, v249, s49, v82
	v_fma_f32 v84, v250, s49, v83
	v_fma_f32 v85, v251, s49, v84
	v_mov_b32_e32 v17, v85
	s_waitcnt vmcnt(32)
; __device__ __forceinline__ unsigned f2bf(float f) { unsigned r; asm("v_cvt_pk_bf16_f32 %0, %1, %1" : "=v"(r) : "v"(f)); return r & 0xffffu; }
; __device__ __forceinline__ void gl1_item(PREF p, int l, int item, bool valid, LAS unsigned char* pl, int sw, int lane) {
;     ...
;             for (int ss = 0; ss < 16; ++ss) { const int s = g4 * 16 + ss; const int i = d ? 63 - s : s; const size_t rowi = (size_t)(row0 + i * rstride);
;                 bc += gv[ss];
;                 const float en = __expf(-bc), ep = __expf(bc);
;                 const float kt = kc[ss] * en, qt = qc[ss] * 0.125f * ep;
;                 const unsigned ktb = f2bf(kt);
;                 sKt[lane * 72 + i] = (bf16_t)ktb;
;                 QK[rowi * 1024 + d * 512 + h * 64 + lane] = (bf16_t)f2bf(qt);
;                 QK[rowi * 1024 + d * 512 + 256 + h * 64 + lane] = (bf16_t)ktb;
	v_mul_f32_e32 v18, 0xbfb8aa3b, v70
	v_mul_f32_e32 v19, 0xbfb8aa3b, v71
	v_mul_f32_e32 v20, 0xbfb8aa3b, v72
	v_mul_f32_e32 v21, 0xbfb8aa3b, v73
	v_mul_f32_e32 v22, 0xbfb8aa3b, v74
	v_mul_f32_e32 v23, 0xbfb8aa3b, v75
	v_mul_f32_e32 v24, 0xbfb8aa3b, v76
	v_mul_f32_e32 v25, 0xbfb8aa3b, v77
	v_mul_f32_e32 v26, 0xbfb8aa3b, v78
	v_mul_f32_e32 v27, 0xbfb8aa3b, v79
	v_mul_f32_e32 v28, 0xbfb8aa3b, v80
	v_mul_f32_e32 v29, 0xbfb8aa3b, v81
	v_mul_f32_e32 v30, 0xbfb8aa3b, v82
	v_mul_f32_e32 v31, 0xbfb8aa3b, v83
	v_mul_f32_e32 v32, 0xbfb8aa3b, v84
	v_mul_f32_e32 v33, 0xbfb8aa3b, v85
	v_exp_f32_e64 v236, -v18
	v_exp_f32_e64 v237, -v19
	v_exp_f32_e64 v238, -v20
	v_exp_f32_e64 v239, -v21
	v_exp_f32_e64 v240, -v22
	v_exp_f32_e64 v241, -v23
	v_exp_f32_e64 v242, -v24
	v_exp_f32_e64 v243, -v25
	v_exp_f32_e64 v244, -v26
	v_exp_f32_e64 v245, -v27
	v_exp_f32_e64 v246, -v28
	v_exp_f32_e64 v247, -v29
	v_exp_f32_e64 v248, -v30
	v_exp_f32_e64 v249, -v31
	v_exp_f32_e64 v250, -v32
	v_exp_f32_e64 v251, -v33
	v_exp_f32_e32 v18, v18
	v_exp_f32_e32 v19, v19
	v_exp_f32_e32 v20, v20
	v_exp_f32_e32 v21, v21
	v_exp_f32_e32 v22, v22
	v_exp_f32_e32 v23, v23
	v_exp_f32_e32 v24, v24
	v_exp_f32_e32 v25, v25
	v_exp_f32_e32 v26, v26
	v_exp_f32_e32 v27, v27
	v_exp_f32_e32 v28, v28
	v_exp_f32_e32 v29, v29
	v_exp_f32_e32 v30, v30
	v_exp_f32_e32 v31, v31
	v_exp_f32_e32 v32, v32
	v_exp_f32_e32 v33, v33
	v_mul_f32_e32 v18, v18, v196
	v_mul_f32_e32 v19, v19, v197
	v_mul_f32_e32 v20, v20, v198
	v_mul_f32_e32 v21, v21, v199
	v_mul_f32_e32 v22, v22, v200
	v_mul_f32_e32 v23, v23, v201
	v_mul_f32_e32 v24, v24, v202
	v_mul_f32_e32 v25, v25, v203
	v_mul_f32_e32 v26, v26, v204
	v_mul_f32_e32 v27, v27, v205
	v_mul_f32_e32 v28, v28, v206
	v_mul_f32_e32 v29, v29, v207
	v_mul_f32_e32 v30, v30, v208
	v_mul_f32_e32 v31, v31, v209
	v_mul_f32_e32 v32, v32, v210
	v_mul_f32_e32 v33, v33, v211
	v_mul_f32_e32 v70, 0x3e000000, v180
	v_mul_f32_e32 v71, 0x3e000000, v181
	v_mul_f32_e32 v72, 0x3e000000, v182
	v_mul_f32_e32 v73, 0x3e000000, v183
	v_mul_f32_e32 v74, 0x3e000000, v184
	v_mul_f32_e32 v75, 0x3e000000, v185
	v_mul_f32_e32 v76, 0x3e000000, v186
	v_mul_f32_e32 v77, 0x3e000000, v187
	v_mul_f32_e32 v78, 0x3e000000, v188
	v_mul_f32_e32 v79, 0x3e000000, v189
	v_mul_f32_e32 v80, 0x3e000000, v190
	v_mul_f32_e32 v81, 0x3e000000, v191
	v_mul_f32_e32 v82, 0x3e000000, v192
	v_mul_f32_e32 v83, 0x3e000000, v193
	v_mul_f32_e32 v84, 0x3e000000, v194
	v_mul_f32_e32 v85, 0x3e000000, v195
	v_mul_f32_e32 v236, v70, v236
	v_mul_f32_e32 v237, v71, v237
	v_mul_f32_e32 v238, v72, v238
	v_mul_f32_e32 v239, v73, v239
	v_mul_f32_e32 v240, v74, v240
	v_mul_f32_e32 v241, v75, v241
	v_mul_f32_e32 v242, v76, v242
	v_mul_f32_e32 v243, v77, v243
	v_mul_f32_e32 v244, v78, v244
	v_mul_f32_e32 v245, v79, v245
	v_mul_f32_e32 v246, v80, v246
	v_mul_f32_e32 v247, v81, v247
	v_mul_f32_e32 v248, v82, v248
	v_mul_f32_e32 v249, v83, v249
	v_mul_f32_e32 v250, v84, v250
	v_mul_f32_e32 v251, v85, v251
	v_cvt_pk_bf16_f32 v18, v18, v236
	v_cvt_pk_bf16_f32 v19, v19, v237
	v_cvt_pk_bf16_f32 v20, v20, v238
	v_cvt_pk_bf16_f32 v21, v21, v239
	v_cvt_pk_bf16_f32 v22, v22, v240
	v_cvt_pk_bf16_f32 v23, v23, v241
	v_cvt_pk_bf16_f32 v24, v24, v242
	v_cvt_pk_bf16_f32 v25, v25, v243
	v_cvt_pk_bf16_f32 v26, v26, v244
	v_cvt_pk_bf16_f32 v27, v27, v245
	v_cvt_pk_bf16_f32 v28, v28, v246
	v_cvt_pk_bf16_f32 v29, v29, v247
	v_cvt_pk_bf16_f32 v30, v30, v248
	v_cvt_pk_bf16_f32 v31, v31, v249
	v_cvt_pk_bf16_f32 v32, v32, v250
	v_cvt_pk_bf16_f32 v33, v33, v251
	ds_write_b16 v60, v18
	v_add_u32_e32 v60, v61, v60
	global_store_short_d16_hi v134, v18, s[4:5]
; __device__ __forceinline__ unsigned f2bf(float f) { unsigned r; asm("v_cvt_pk_bf16_f32 %0, %1, %1" : "=v"(r) : "v"(f)); return r & 0xffffu; }
; __device__ __forceinline__ void gl1_item(PREF p, int l, int item, bool valid, LAS unsigned char* pl, int sw, int lane) {
;     ...
;             for (int ss = 0; ss < 16; ++ss) { const int s = g4 * 16 + ss; const int i = d ? 63 - s : s; const size_t rowi = (size_t)(row0 + i * rstride);
;                 bc += gv[ss];
;                 const float en = __expf(-bc), ep = __expf(bc);
;                 const float kt = kc[ss] * en, qt = qc[ss] * 0.125f * ep;
;                 const unsigned ktb = f2bf(kt);
;                 sKt[lane * 72 + i] = (bf16_t)ktb;
;                 QK[rowi * 1024 + d * 512 + h * 64 + lane] = (bf16_t)f2bf(qt);
;                 QK[rowi * 1024 + d * 512 + 256 + h * 64 + lane] = (bf16_t)ktb;
;             }
; #pragma unroll
;             for (int ss = 0; ss < 16; ++ss) { qc[ss] = bf2f(__builtin_bit_cast(unsigned, qn[ss])); kc[ss] = bf2f(__builtin_bit_cast(unsigned, kn[ss])); }
;         }
;         const float Dv = __expf(bc);
;         sD[lane] = Dv; GLD[(size_t)(seq * NCH + cj) * 64 + lane] = Dv;
	global_store_short v134, v18, s[4:5] offset:512
	s_add_u32 s4, s4, s56
	s_addc_u32 s5, s5, s3
	ds_write_b16 v60, v19
	v_add_u32_e32 v60, v61, v60
	global_store_short_d16_hi v134, v19, s[4:5]
	global_store_short v134, v19, s[4:5] offset:512
	s_add_u32 s4, s4, s56
	s_addc_u32 s5, s5, s3
	ds_write_b16 v60, v20
	v_add_u32_e32 v60, v61, v60
	global_store_short_d16_hi v134, v20, s[4:5]
	global_store_short v134, v20, s[4:5] offset:512
	s_add_u32 s4, s4, s56
	s_addc_u32 s5, s5, s3
	ds_write_b16 v60, v21
	v_add_u32_e32 v60, v61, v60
	global_store_short_d16_hi v134, v21, s[4:5]
	global_store_short v134, v21, s[4:5] offset:512
	s_add_u32 s4, s4, s56
	s_addc_u32 s5, s5, s3
	ds_write_b16 v60, v22
	v_add_u32_e32 v60, v61, v60
	global_store_short_d16_hi v134, v22, s[4:5]
	global_store_short v134, v22, s[4:5] offset:512
	s_add_u32 s4, s4, s56
	s_addc_u32 s5, s5, s3
	ds_write_b16 v60, v23
	v_add_u32_e32 v60, v61, v60
	global_store_short_d16_hi v134, v23, s[4:5]
	global_store_short v134, v23, s[4:5] offset:512
	s_add_u32 s4, s4, s56
	s_addc_u32 s5, s5, s3
	ds_write_b16 v60, v24
	v_add_u32_e32 v60, v61, v60
	global_store_short_d16_hi v134, v24, s[4:5]
	global_store_short v134, v24, s[4:5] offset:512
	s_add_u32 s4, s4, s56
	s_addc_u32 s5, s5, s3
	ds_write_b16 v60, v25
	v_add_u32_e32 v60, v61, v60
	global_store_short_d16_hi v134, v25, s[4:5]
	global_store_short v134, v25, s[4:5] offset:512
	s_add_u32 s4, s4, s56
	s_addc_u32 s5, s5, s3
	ds_write_b16 v60, v26
	v_add_u32_e32 v60, v61, v60
	global_store_short_d16_hi v134, v26, s[4:5]
	global_store_short v134, v26, s[4:5] offset:512
	s_add_u32 s4, s4, s56
	s_addc_u32 s5, s5, s3
	ds_write_b16 v60, v27
	v_add_u32_e32 v60, v61, v60
	global_store_short_d16_hi v134, v27, s[4:5]
	global_store_short v134, v27, s[4:5] offset:512
	s_add_u32 s4, s4, s56
	s_addc_u32 s5, s5, s3
	ds_write_b16 v60, v28
	v_add_u32_e32 v60, v61, v60
	global_store_short_d16_hi v134, v28, s[4:5]
	global_store_short v134, v28, s[4:5] offset:512
	s_add_u32 s4, s4, s56
	s_addc_u32 s5, s5, s3
	ds_write_b16 v60, v29
	v_add_u32_e32 v60, v61, v60
	global_store_short_d16_hi v134, v29, s[4:5]
	global_store_short v134, v29, s[4:5] offset:512
	s_add_u32 s4, s4, s56
	s_addc_u32 s5, s5, s3
	ds_write_b16 v60, v30
	v_add_u32_e32 v60, v61, v60
	global_store_short_d16_hi v134, v30, s[4:5]
	global_store_short v134, v30, s[4:5] offset:512
	s_add_u32 s4, s4, s56
	s_addc_u32 s5, s5, s3
	ds_write_b16 v60, v31
	v_add_u32_e32 v60, v61, v60
	global_store_short_d16_hi v134, v31, s[4:5]
	global_store_short v134, v31, s[4:5] offset:512
	s_add_u32 s4, s4, s56
	s_addc_u32 s5, s5, s3
	ds_write_b16 v60, v32
	v_add_u32_e32 v60, v61, v60
	global_store_short_d16_hi v134, v32, s[4:5]
	global_store_short v134, v32, s[4:5] offset:512
	s_add_u32 s4, s4, s56
	s_addc_u32 s5, s5, s3
	ds_write_b16 v60, v33
	v_add_u32_e32 v60, v61, v60
	global_store_short_d16_hi v134, v33, s[4:5]
	global_store_short v134, v33, s[4:5] offset:512
	s_add_u32 s4, s4, s56
	s_addc_u32 s5, s5, s3
	v_mul_f32_e32 v18, 0x3fb8aa3b, v17
	v_exp_f32_e32 v18, v18
	v_readlane_b32 s50, v253, 55
	v_readlane_b32 s51, v253, 56
	v_readlane_b32 s45, v254, 11
	s_nop 3
	s_load_dwordx2 s[46:47], s[50:51], 0xc0
	s_and_b32 s48, s38, 1
	s_lshr_b32 s45, s45, 7
	s_mul_i32 s45, s45, 0x9200
	s_lshl_b32 s48, s48, 8
	s_add_i32 s45, s45, s48
	v_lshl_add_u32 v86, v64, 2, s45
	ds_write_b32 v86, v18 offset:36864
	s_or_b32 s45, s42, s38
	s_mulk_i32 s45, 0x104
	s_add_i32 s45, s45, s41
	s_lshl_b32 s45, s45, 8
	s_waitcnt lgkmcnt(0)
	s_add_u32 s46, s46, 0xd00000
	s_addc_u32 s47, s47, 0
	s_add_u32 s46, s46, s45
	s_addc_u32 s47, s47, 0
	global_store_dword v135, v18, s[46:47]
